# v93 + P1 GELU epilogue: -log2(e) folded into the two polynomial constants (one v_mul less per element, same formula)
# speedup vs baseline: 1.0058x; 1.0040x over previous
; #define ROWS8 _Pragma("unroll") for (int ai = 0; ai < 2; ++ai) _Pragma("unroll") for (int m = 0; m < 4; ++m) if (ai == 0 || !hf)
; #define PK8(v0, v1) ({ const u32x2 h0_ = pk4(v0), h1_ = pk4(v1); (u32x4){h0_.x, h0_.y, h1_.x, h1_.y}; })
; #define LOAD_COLP_RS(rsc, ssqp, invn) f32x4 rsc[2][2]; COLS4 rsc[bj][n] = *(const f32x4*)((ssqp) + colp + bj * HALF + n * 4); \
;         COLS4 rsc[bj][n] = (f32x4){rstd_of(rsc[bj][n][0], invn), rstd_of(rsc[bj][n][1], invn), rstd_of(rsc[bj][n][2], invn), rstd_of(rsc[bj][n][3], invn)}
; DI float gelu_tanh(float x) { const float t = x * (1.5957691216f + 0.0713548163f * x * x); return x * __builtin_amdgcn_rcpf(1.f + __builtin_amdgcn_exp2f(-1.4426950409f * t)); }
;     DI void operator()(const Acc& acc, const Unit& u, int wr, int wc, int fr, int fq) const {
;     ...
;                 float* ssqv = SSQ(1 + sqo);
;                 LOAD_COLP_RS(rsc, SSQ(0), 1.f / 2048.f);
; #pragma unroll
;                 for (int bj = 0; bj < 2; ++bj) { const int cc = colp + bj * HALF;
;                     f32x4 sq0 = {0.f, 0.f, 0.f, 0.f}, sq1 = {0.f, 0.f, 0.f, 0.f};
;                     ROWS8 { const int r = row0 + ai * HALF + m * 16; f32x4 v0 = acc[ai][bj][m][0] * rsc[bj][0], v1 = acc[ai][bj][m][1] * rsc[bj][1];
;                         v0[0] = gelu_tanh(v0[0]); v0[1] = gelu_tanh(v0[1]); v0[2] = gelu_tanh(v0[2]); v0[3] = gelu_tanh(v0[3]);
;                         v1[0] = gelu_tanh(v1[0]); v1[1] = gelu_tanh(v1[1]); v1[2] = gelu_tanh(v1[2]); v1[3] = gelu_tanh(v1[3]);
;                         sq0 += v0 * v0; sq1 += v1 * v1; *(u32x4*)(WSB(OFF_VT) + (size_t)r * 8192 + cc) = PK8(v0, v1); }
.Lpeel_0_exit:
	v_lshl_add_u32 v158, s4, 8, v223
	v_lshl_add_u32 v156, s73, 8, v225
	v_or_b32_e32 v164, 16, v158
	v_or_b32_e32 v162, 32, v158
	v_or_b32_e32 v160, 48, v158
	s_cmp_lg_u32 s74, 0
	v_ashrrev_i32_e32 v157, 31, v156
	v_ashrrev_i32_e32 v159, 31, v158
	v_ashrrev_i32_e32 v165, 31, v164
	v_ashrrev_i32_e32 v163, 31, v162
	v_ashrrev_i32_e32 v161, 31, v160
	s_cbranch_scc0 .LBB0_362
	v_lshlrev_b64 v[136:137], 2, v[156:157]
	v_lshl_add_u64 v[132:133], s[16:17], 0, v[136:137]
	global_load_dwordx4 v[166:169], v[132:133], off
	global_load_dwordx4 v[172:175], v[132:133], off offset:16
	v_lshlrev_b64 v[128:129], 14, v[158:159]
	v_lshlrev_b64 v[170:171], 1, v[156:157]
	v_lshl_add_u64 v[138:139], s[20:21], 0, v[128:129]
	v_lshl_add_u64 v[138:139], v[138:139], 0, v[170:171]
	global_load_dwordx4 v[128:131], v[132:133], off offset:528
	s_nop 0
	global_load_dwordx4 v[132:135], v[132:133], off offset:512
	v_lshl_add_u64 v[136:137], s[18:19], 0, v[136:137]
	s_waitcnt vmcnt(0)
	v_fmamk_f32 v166, v166, 0x3a000000, v233
	v_fmamk_f32 v167, v167, 0x3a000000, v233
	v_fmamk_f32 v168, v168, 0x3a000000, v233
	v_fmamk_f32 v169, v169, 0x3a000000, v233
	v_rsq_f32_e32 v190, v166
	v_rsq_f32_e32 v191, v167
	v_rsq_f32_e32 v186, v168
	v_rsq_f32_e32 v187, v169
	v_fmamk_f32 v172, v172, 0x3a000000, v233
	v_fmamk_f32 v173, v173, 0x3a000000, v233
	v_fmamk_f32 v174, v174, 0x3a000000, v233
	v_fmamk_f32 v175, v175, 0x3a000000, v233
	v_rsq_f32_e32 v182, v172
	v_rsq_f32_e32 v184, v174
	v_rsq_f32_e32 v185, v175
	v_rsq_f32_e32 v183, v173
	v_pk_mul_f32 v[168:169], v[124:125], v[190:191]
	v_pk_mul_f32 v[166:167], v[126:127], v[186:187]
	v_mul_f32_e32 v178, 0xbdd2d3e7, v168
	v_mul_f32_e32 v179, 0xbdd2d3e7, v169
	v_mul_f32_e32 v192, 0xbdd2d3e7, v166
	v_mul_f32_e32 v193, 0xbdd2d3e7, v167
	v_fmaak_f32 v178, v168, v178, 0xc0135761
	v_fmaak_f32 v179, v169, v179, 0xc0135761
	v_pk_mul_f32 v[172:173], v[122:123], v[184:185]
	v_pk_mul_f32 v[174:175], v[120:121], v[182:183]
	v_fmaak_f32 v192, v166, v192, 0xc0135761
	v_fmaak_f32 v193, v167, v193, 0xc0135761
	v_mul_f32_e32 v178, v168, v178
	v_mul_f32_e32 v179, v169, v179
	v_mul_f32_e32 v196, 0xbdd2d3e7, v174
	v_mul_f32_e32 v197, 0xbdd2d3e7, v175
	v_mul_f32_e32 v198, 0xbdd2d3e7, v172
	v_mul_f32_e32 v199, 0xbdd2d3e7, v173
	v_mul_f32_e32 v192, v166, v192
	v_mul_f32_e32 v193, v167, v193
	v_fmaak_f32 v196, v174, v196, 0xc0135761
	v_fmaak_f32 v197, v175, v197, 0xc0135761
	v_fmaak_f32 v198, v172, v198, 0xc0135761
	v_fmaak_f32 v199, v173, v199, 0xc0135761
	v_exp_f32_e32 v178, v178
	v_exp_f32_e32 v179, v179
	v_mul_f32_e32 v196, v174, v196
	v_mul_f32_e32 v197, v175, v197
	v_mul_f32_e32 v198, v172, v198
	v_mul_f32_e32 v199, v173, v199
	v_exp_f32_e32 v192, v192
	v_exp_f32_e32 v193, v193
	v_exp_f32_e32 v196, v196
	v_exp_f32_e32 v197, v197
	v_exp_f32_e32 v198, v198
	v_exp_f32_e32 v199, v199
	v_add_f32_e32 v178, 1.0, v178
	v_add_f32_e32 v179, 1.0, v179
	v_add_f32_e32 v201, 1.0, v192
	v_add_f32_e32 v202, 1.0, v193
	v_rcp_f32_e32 v192, v178
	v_rcp_f32_e32 v193, v179
	v_add_f32_e32 v196, 1.0, v196
	v_add_f32_e32 v197, 1.0, v197
	v_add_f32_e32 v198, 1.0, v198
	v_add_f32_e32 v199, 1.0, v199
	v_pk_mul_f32 v[194:195], v[104:105], v[182:183]
	v_rcp_f32_e32 v178, v201
	v_rcp_f32_e32 v179, v202
	v_rcp_f32_e32 v196, v196
	v_rcp_f32_e32 v198, v198
	v_rcp_f32_e32 v199, v199
	v_rcp_f32_e32 v197, v197
	v_pk_mul_f32 v[202:203], v[168:169], v[192:193]
	v_mul_f32_e32 v192, 0xbdd2d3e7, v194
	v_fmaak_f32 v192, v194, v192, 0xc0135761
	v_mul_f32_e32 v192, v194, v192
	v_pk_mul_f32 v[178:179], v[166:167], v[178:179]
	v_pk_mul_f32 v[172:173], v[172:173], v[198:199]
	v_pk_mul_f32 v[174:175], v[174:175], v[196:197]
	v_pk_mul_f32 v[176:177], v[110:111], v[186:187]
	v_pk_mul_f32 v[188:189], v[106:107], v[184:185]
	v_cvt_pk_bf16_f32 v166, v202, v203
	v_cvt_pk_bf16_f32 v167, v178, v179
	v_cvt_pk_bf16_f32 v168, v174, v175
	v_cvt_pk_bf16_f32 v169, v172, v173
	v_exp_f32_e32 v192, v192
	global_store_dwordx4 v[138:139], v[166:169], off
	v_mul_f32_e32 v193, 0xbdd2d3e7, v188
	v_fmaak_f32 v193, v188, v193, 0xc0135761
	v_mul_f32_e32 v168, 0xbdd2d3e7, v176
	v_mul_f32_e32 v169, 0xbdd2d3e7, v177
	v_fmaak_f32 v168, v176, v168, 0xc0135761
	v_fmaak_f32 v169, v177, v169, 0xc0135761
	v_mul_f32_e32 v197, 0xbdd2d3e7, v189
	v_mul_f32_e32 v168, v176, v168
	v_mul_f32_e32 v169, v177, v169
	v_mul_f32_e32 v193, v188, v193
	v_fmaak_f32 v197, v189, v197, 0xc0135761
	v_add_f32_e32 v192, 1.0, v192
	v_mul_f32_e32 v197, v189, v197
	v_exp_f32_e32 v168, v168
	v_exp_f32_e32 v169, v169
	v_rcp_f32_e32 v196, v192
	v_mul_f32_e32 v192, 0xbdd2d3e7, v195
	v_exp_f32_e32 v193, v193
	v_fmaak_f32 v192, v195, v192, 0xc0135761
	v_exp_f32_e32 v197, v197
	v_mul_f32_e32 v192, v195, v192
	v_add_f32_e32 v168, 1.0, v168
	v_add_f32_e32 v169, 1.0, v169
	v_exp_f32_e32 v192, v192
	v_add_f32_e32 v193, 1.0, v193
	v_pk_mul_f32 v[180:181], v[108:109], v[190:191]
	v_rcp_f32_e32 v168, v168
	v_rcp_f32_e32 v169, v169
	v_rcp_f32_e32 v198, v193
	v_add_f32_e32 v193, 1.0, v197
	v_mul_f32_e32 v200, 0xbdd2d3e7, v180
	v_mul_f32_e32 v167, 0xbdd2d3e7, v181
	v_rcp_f32_e32 v199, v193
	v_fmaak_f32 v200, v180, v200, 0xc0135761
	v_fmaak_f32 v167, v181, v167, 0xc0135761
	v_mul_f32_e32 v200, v180, v200
	v_mul_f32_e32 v167, v181, v167
	v_add_f32_e32 v192, 1.0, v192
	v_rcp_f32_e32 v197, v192
	v_pk_mul_f32 v[192:193], v[176:177], v[168:169]
	v_pk_mul_f32 v[168:169], v[92:93], v[190:191]
	v_exp_f32_e32 v200, v200
	v_exp_f32_e32 v167, v167
	v_pk_mul_f32 v[176:177], v[188:189], v[198:199]
	v_mul_f32_e32 v188, 0xbdd2d3e7, v168
	v_fmaak_f32 v188, v168, v188, 0xc0135761
	v_mul_f32_e32 v188, v168, v188
	v_add_f32_e32 v166, 1.0, v200
	v_add_f32_e32 v167, 1.0, v167
; DI float gelu_tanh(float x) { const float t = x * (1.5957691216f + 0.0713548163f * x * x); return x * __builtin_amdgcn_rcpf(1.f + __builtin_amdgcn_exp2f(-1.4426950409f * t)); }
; #define ROWS8 _Pragma("unroll") for (int ai = 0; ai < 2; ++ai) _Pragma("unroll") for (int m = 0; m < 4; ++m) if (ai == 0 || !hf)
; #define PK8(v0, v1) ({ const u32x2 h0_ = pk4(v0), h1_ = pk4(v1); (u32x4){h0_.x, h0_.y, h1_.x, h1_.y}; })
;     DI void operator()(const Acc& acc, const Unit& u, int wr, int wc, int fr, int fq) const {
;     ...
;                     ROWS8 { const int r = row0 + ai * HALF + m * 16; f32x4 v0 = acc[ai][bj][m][0] * rsc[bj][0], v1 = acc[ai][bj][m][1] * rsc[bj][1];
;                         v0[0] = gelu_tanh(v0[0]); v0[1] = gelu_tanh(v0[1]); v0[2] = gelu_tanh(v0[2]); v0[3] = gelu_tanh(v0[3]);
;                         v1[0] = gelu_tanh(v1[0]); v1[1] = gelu_tanh(v1[1]); v1[2] = gelu_tanh(v1[2]); v1[3] = gelu_tanh(v1[3]);
;                         sq0 += v0 * v0; sq1 += v1 * v1; *(u32x4*)(WSB(OFF_VT) + (size_t)r * 8192 + cc) = PK8(v0, v1); }
	v_exp_f32_e32 v198, v188
	v_pk_mul_f32 v[188:189], v[94:95], v[186:187]
	v_mul_f32_e32 v199, 0xbdd2d3e7, v169
	v_rcp_f32_e32 v166, v166
	v_rcp_f32_e32 v167, v167
	v_fmaak_f32 v199, v169, v199, 0xc0135761
	v_mul_f32_e32 v200, 0xbdd2d3e7, v188
	v_mul_f32_e32 v199, v169, v199
	v_fmaak_f32 v200, v188, v200, 0xc0135761
	v_mul_f32_e32 v200, v188, v200
	v_exp_f32_e32 v199, v199
	v_pk_mul_f32 v[210:211], v[180:181], v[166:167]
	v_lshlrev_b64 v[166:167], 14, v[164:165]
	v_exp_f32_e32 v204, v200
	v_pk_mul_f32 v[180:181], v[194:195], v[196:197]
	v_lshl_add_u64 v[166:167], s[20:21], 0, v[166:167]
	v_cvt_pk_bf16_f32 v194, v210, v211
	v_cvt_pk_bf16_f32 v195, v192, v193
	v_cvt_pk_bf16_f32 v196, v180, v181
	v_cvt_pk_bf16_f32 v197, v176, v177
	v_lshl_add_u64 v[166:167], v[166:167], 0, v[170:171]
	v_add_f32_e32 v198, 1.0, v198
	global_store_dwordx4 v[166:167], v[194:197], off
	v_rcp_f32_e32 v200, v198
	v_add_f32_e32 v198, 1.0, v199
	v_pk_mul_f32 v[194:195], v[90:91], v[184:185]
	v_pk_mul_f32 v[196:197], v[88:89], v[182:183]
	v_rcp_f32_e32 v201, v198
	v_add_f32_e32 v198, 1.0, v204
	v_mul_f32_e32 v199, 0xbdd2d3e7, v189
	v_mul_f32_e32 v204, 0xbdd2d3e7, v196
	v_mul_f32_e32 v205, 0xbdd2d3e7, v197
	v_mul_f32_e32 v206, 0xbdd2d3e7, v194
	v_mul_f32_e32 v207, 0xbdd2d3e7, v195
	v_fmaak_f32 v199, v189, v199, 0xc0135761
	v_fmaak_f32 v204, v196, v204, 0xc0135761
	v_fmaak_f32 v205, v197, v205, 0xc0135761
	v_fmaak_f32 v206, v194, v206, 0xc0135761
	v_fmaak_f32 v207, v195, v207, 0xc0135761
	v_mul_f32_e32 v199, v189, v199
	v_mul_f32_e32 v204, v196, v204
	v_mul_f32_e32 v205, v197, v205
	v_mul_f32_e32 v206, v194, v206
	v_mul_f32_e32 v207, v195, v207
	v_exp_f32_e32 v199, v199
	v_exp_f32_e32 v204, v204
	v_exp_f32_e32 v205, v205
	v_exp_f32_e32 v206, v206
	v_exp_f32_e32 v207, v207
	v_add_f32_e32 v199, 1.0, v199
	v_add_f32_e32 v204, 1.0, v204
	v_add_f32_e32 v205, 1.0, v205
	v_add_f32_e32 v206, 1.0, v206
	v_add_f32_e32 v207, 1.0, v207
	v_rcp_f32_e32 v198, v198
	v_rcp_f32_e32 v199, v199
	v_rcp_f32_e32 v204, v204
	v_rcp_f32_e32 v206, v206
	v_rcp_f32_e32 v207, v207
	v_rcp_f32_e32 v205, v205
	v_pk_mul_f32 v[198:199], v[188:189], v[198:199]
	v_pk_mul_f32 v[212:213], v[168:169], v[200:201]
	v_pk_mul_f32 v[188:189], v[194:195], v[206:207]
	v_pk_mul_f32 v[194:195], v[196:197], v[204:205]
	v_pk_mul_f32 v[196:197], v[76:77], v[190:191]
	v_lshlrev_b64 v[168:169], 14, v[162:163]
	v_mul_f32_e32 v200, 0xbdd2d3e7, v196
	v_fmaak_f32 v200, v196, v200, 0xc0135761
	v_lshl_add_u64 v[168:169], s[20:21], 0, v[168:169]
	v_mul_f32_e32 v200, v196, v200
	v_cvt_pk_bf16_f32 v204, v212, v213
	v_cvt_pk_bf16_f32 v205, v198, v199
	v_cvt_pk_bf16_f32 v206, v194, v195
	v_cvt_pk_bf16_f32 v207, v188, v189
	v_lshl_add_u64 v[168:169], v[168:169], 0, v[170:171]
	global_store_dwordx4 v[168:169], v[204:207], off
	v_pk_mul_f32 v[208:209], v[72:73], v[182:183]
	s_nop 0
	v_exp_f32_e32 v204, v200
	v_pk_mul_f32 v[200:201], v[78:79], v[186:187]
	v_mul_f32_e32 v205, 0xbdd2d3e7, v197
	v_fmaak_f32 v205, v197, v205, 0xc0135761
	v_mul_f32_e32 v214, 0xbdd2d3e7, v200
	v_mul_f32_e32 v205, v197, v205
	v_fmaak_f32 v214, v200, v214, 0xc0135761
	v_mul_f32_e32 v214, v200, v214
	v_exp_f32_e32 v205, v205
	v_exp_f32_e32 v216, v214
	v_add_f32_e32 v204, 1.0, v204
	v_rcp_f32_e32 v214, v204
	v_add_f32_e32 v204, 1.0, v205
	v_pk_mul_f32 v[206:207], v[74:75], v[184:185]
	v_rcp_f32_e32 v215, v204
	v_add_f32_e32 v204, 1.0, v216
	v_mul_f32_e32 v205, 0xbdd2d3e7, v201
	v_mul_f32_e32 v216, 0xbdd2d3e7, v208
	v_mul_f32_e32 v217, 0xbdd2d3e7, v209
	v_fmaak_f32 v205, v201, v205, 0xc0135761
	v_fmaak_f32 v216, v208, v216, 0xc0135761
	v_fmaak_f32 v217, v209, v217, 0xc0135761
	v_mul_f32_e32 v218, 0xbdd2d3e7, v206
	v_mul_f32_e32 v219, 0xbdd2d3e7, v207
	v_mul_f32_e32 v205, v201, v205
	v_mul_f32_e32 v216, v208, v216
	v_mul_f32_e32 v217, v209, v217
	v_fmaak_f32 v218, v206, v218, 0xc0135761
	v_fmaak_f32 v219, v207, v219, 0xc0135761
	v_mul_f32_e32 v218, v206, v218
	v_mul_f32_e32 v219, v207, v219
	v_exp_f32_e32 v205, v205
	v_exp_f32_e32 v216, v216
	v_exp_f32_e32 v217, v217
	v_exp_f32_e32 v218, v218
	v_exp_f32_e32 v219, v219
	v_add_f32_e32 v205, 1.0, v205
	v_add_f32_e32 v216, 1.0, v216
	v_add_f32_e32 v217, 1.0, v217
	v_rcp_f32_e32 v204, v204
	v_rcp_f32_e32 v205, v205
	v_rcp_f32_e32 v216, v216
	v_add_f32_e32 v218, 1.0, v218
	v_add_f32_e32 v219, 1.0, v219
	v_rcp_f32_e32 v217, v217
	v_rcp_f32_e32 v218, v218
	v_rcp_f32_e32 v219, v219
	v_pk_mul_f32 v[204:205], v[200:201], v[204:205]
	v_pk_mul_f32 v[200:201], v[208:209], v[216:217]
	v_lshlrev_b64 v[216:217], 14, v[160:161]
	v_pk_mul_f32 v[214:215], v[196:197], v[214:215]
	v_pk_mul_f32 v[196:197], v[206:207], v[218:219]
	v_lshl_add_u64 v[216:217], s[20:21], 0, v[216:217]
	v_cvt_pk_bf16_f32 v206, v214, v215
	v_cvt_pk_bf16_f32 v207, v204, v205
	v_cvt_pk_bf16_f32 v208, v200, v201
	v_cvt_pk_bf16_f32 v209, v196, v197
	v_lshl_add_u64 v[170:171], v[216:217], 0, v[170:171]
	global_store_dwordx4 v[170:171], v[206:209], off
	s_nop 1
	v_pk_mul_f32 v[206:207], v[210:211], v[210:211]
	s_nop 0
	v_pk_fma_f32 v[202:203], v[202:203], v[202:203], v[206:207]
	s_nop 0
	v_pk_fma_f32 v[202:203], v[212:213], v[212:213], v[202:203]
	v_pk_mul_f32 v[212:213], v[58:59], v[184:185]
	v_pk_fma_f32 v[208:209], v[214:215], v[214:215], v[202:203]
	v_pk_mul_f32 v[202:203], v[60:61], v[190:191]
	v_pk_mul_f32 v[214:215], v[56:57], v[182:183]
	v_mul_f32_e32 v206, 0xbdd2d3e7, v202
	v_fmaak_f32 v206, v202, v206, 0xc0135761
	v_mul_f32_e32 v206, v202, v206
	v_exp_f32_e32 v210, v206
	v_pk_mul_f32 v[206:207], v[62:63], v[186:187]
	v_mul_f32_e32 v211, 0xbdd2d3e7, v203
	v_fmaak_f32 v211, v203, v211, 0xc0135761
	v_mul_f32_e32 v216, 0xbdd2d3e7, v206
	v_mul_f32_e32 v211, v203, v211
; DI float gelu_tanh(float x) { const float t = x * (1.5957691216f + 0.0713548163f * x * x); return x * __builtin_amdgcn_rcpf(1.f + __builtin_amdgcn_exp2f(-1.4426950409f * t)); }
; #define ROWS8 _Pragma("unroll") for (int ai = 0; ai < 2; ++ai) _Pragma("unroll") for (int m = 0; m < 4; ++m) if (ai == 0 || !hf)
; #define PK8(v0, v1) ({ const u32x2 h0_ = pk4(v0), h1_ = pk4(v1); (u32x4){h0_.x, h0_.y, h1_.x, h1_.y}; })
;     DI void operator()(const Acc& acc, const Unit& u, int wr, int wc, int fr, int fq) const {
;     ...
;                     ROWS8 { const int r = row0 + ai * HALF + m * 16; f32x4 v0 = acc[ai][bj][m][0] * rsc[bj][0], v1 = acc[ai][bj][m][1] * rsc[bj][1];
;                         v0[0] = gelu_tanh(v0[0]); v0[1] = gelu_tanh(v0[1]); v0[2] = gelu_tanh(v0[2]); v0[3] = gelu_tanh(v0[3]);
;                         v1[0] = gelu_tanh(v1[0]); v1[1] = gelu_tanh(v1[1]); v1[2] = gelu_tanh(v1[2]); v1[3] = gelu_tanh(v1[3]);
;                         sq0 += v0 * v0; sq1 += v1 * v1; *(u32x4*)(WSB(OFF_VT) + (size_t)r * 8192 + cc) = PK8(v0, v1); }
	v_fmaak_f32 v216, v206, v216, 0xc0135761
	v_mul_f32_e32 v216, v206, v216
	v_exp_f32_e32 v211, v211
	v_exp_f32_e32 v218, v216
	v_add_f32_e32 v210, 1.0, v210
	v_rcp_f32_e32 v216, v210
	v_add_f32_e32 v210, 1.0, v211
	v_rcp_f32_e32 v217, v210
	v_add_f32_e32 v210, 1.0, v218
	v_mul_f32_e32 v211, 0xbdd2d3e7, v207
	v_mul_f32_e32 v218, 0xbdd2d3e7, v214
	v_mul_f32_e32 v219, 0xbdd2d3e7, v215
	v_mul_f32_e32 v220, 0xbdd2d3e7, v212
	v_mul_f32_e32 v221, 0xbdd2d3e7, v213
	v_fmaak_f32 v211, v207, v211, 0xc0135761
	v_fmaak_f32 v218, v214, v218, 0xc0135761
	v_fmaak_f32 v219, v215, v219, 0xc0135761
	v_fmaak_f32 v220, v212, v220, 0xc0135761
	v_fmaak_f32 v221, v213, v221, 0xc0135761
	v_mul_f32_e32 v211, v207, v211
	v_mul_f32_e32 v218, v214, v218
	v_mul_f32_e32 v219, v215, v219
	v_mul_f32_e32 v220, v212, v220
	v_mul_f32_e32 v221, v213, v221
	v_exp_f32_e32 v211, v211
	v_exp_f32_e32 v218, v218
	v_exp_f32_e32 v219, v219
	v_exp_f32_e32 v220, v220
	v_exp_f32_e32 v221, v221
	v_add_f32_e32 v211, 1.0, v211
	v_add_f32_e32 v218, 1.0, v218
	v_add_f32_e32 v219, 1.0, v219
	v_add_f32_e32 v220, 1.0, v220
	v_add_f32_e32 v221, 1.0, v221
	v_rcp_f32_e32 v210, v210
	v_rcp_f32_e32 v211, v211
	v_rcp_f32_e32 v218, v218
	v_rcp_f32_e32 v220, v220
	v_rcp_f32_e32 v221, v221
	v_rcp_f32_e32 v219, v219
	v_pk_mul_f32 v[216:217], v[202:203], v[216:217]
	v_pk_mul_f32 v[210:211], v[206:207], v[210:211]
	v_pk_mul_f32 v[202:203], v[212:213], v[220:221]
	v_pk_mul_f32 v[206:207], v[214:215], v[218:219]
	v_pk_fma_f32 v[218:219], v[216:217], v[216:217], v[208:209]
	v_add_co_u32_e32 v208, vcc, s69, v138
	v_cvt_pk_bf16_f32 v212, v216, v217
	v_cvt_pk_bf16_f32 v213, v210, v211
	v_cvt_pk_bf16_f32 v214, v206, v207
	v_cvt_pk_bf16_f32 v215, v202, v203
	v_addc_co_u32_e32 v209, vcc, 0, v139, vcc
	global_store_dwordx4 v[208:209], v[212:215], off
	v_pk_mul_f32 v[208:209], v[44:45], v[190:191]
	v_pk_mul_f32 v[220:221], v[40:41], v[182:183]
	v_mul_f32_e32 v212, 0xbdd2d3e7, v208
	v_fmaak_f32 v212, v208, v212, 0xc0135761
	v_mul_f32_e32 v212, v208, v212
	v_exp_f32_e32 v216, v212
	v_pk_mul_f32 v[212:213], v[46:47], v[186:187]
	v_pk_mul_f32 v[214:215], v[42:43], v[184:185]
	v_mul_f32_e32 v234, 0xbdd2d3e7, v213
	v_fmaak_f32 v234, v213, v234, 0xc0135761
	v_mul_f32_e32 v222, 0xbdd2d3e7, v212
	v_mul_f32_e32 v234, v213, v234
	v_fmaak_f32 v222, v212, v222, 0xc0135761
	v_mul_f32_e32 v222, v212, v222
	v_exp_f32_e32 v235, v234
	v_mul_f32_e32 v234, 0xbdd2d3e7, v220
	v_fmaak_f32 v234, v220, v234, 0xc0135761
	v_exp_f32_e32 v222, v222
	v_mul_f32_e32 v234, v220, v234
	v_exp_f32_e32 v236, v234
	v_add_f32_e32 v222, 1.0, v222
	v_rcp_f32_e32 v234, v222
	v_add_f32_e32 v222, 1.0, v235
	v_rcp_f32_e32 v235, v222
	v_add_f32_e32 v222, 1.0, v236
	v_mul_f32_e32 v237, 0xbdd2d3e7, v214
	v_mul_f32_e32 v217, 0xbdd2d3e7, v209
	v_rcp_f32_e32 v236, v222
	v_mul_f32_e32 v222, 0xbdd2d3e7, v221
	v_fmaak_f32 v237, v214, v237, 0xc0135761
	v_mul_f32_e32 v238, 0xbdd2d3e7, v215
	v_fmaak_f32 v217, v209, v217, 0xc0135761
	v_fmaak_f32 v222, v221, v222, 0xc0135761
	v_mul_f32_e32 v237, v214, v237
	v_fmaak_f32 v238, v215, v238, 0xc0135761
	v_mul_f32_e32 v217, v209, v217
	v_mul_f32_e32 v222, v221, v222
	v_mul_f32_e32 v238, v215, v238
	v_exp_f32_e32 v237, v237
	v_exp_f32_e32 v217, v217
	v_exp_f32_e32 v222, v222
	v_exp_f32_e32 v239, v238
	v_add_f32_e32 v237, 1.0, v237
	v_add_f32_e32 v216, 1.0, v216
	v_add_f32_e32 v217, 1.0, v217
	v_add_f32_e32 v222, 1.0, v222
	v_rcp_f32_e32 v238, v237
	v_add_f32_e32 v237, 1.0, v239
	v_rcp_f32_e32 v216, v216
	v_rcp_f32_e32 v217, v217
	v_rcp_f32_e32 v239, v237
	v_rcp_f32_e32 v237, v222
	v_pk_mul_f32 v[240:241], v[208:209], v[216:217]
	v_pk_mul_f32 v[216:217], v[212:213], v[234:235]
	v_pk_mul_f32 v[208:209], v[214:215], v[238:239]
	v_pk_mul_f32 v[212:213], v[220:221], v[236:237]
	v_add_co_u32_e32 v214, vcc, s70, v138
	v_pk_fma_f32 v[234:235], v[240:241], v[240:241], v[218:219]
	v_cvt_pk_bf16_f32 v218, v240, v241
	v_cvt_pk_bf16_f32 v219, v216, v217
	v_cvt_pk_bf16_f32 v220, v212, v213
	v_cvt_pk_bf16_f32 v221, v208, v209
	v_addc_co_u32_e32 v215, vcc, 0, v139, vcc
	global_store_dwordx4 v[214:215], v[218:221], off
	v_pk_mul_f32 v[214:215], v[28:29], v[190:191]
	v_pk_mul_f32 v[238:239], v[24:25], v[182:183]
	v_mul_f32_e32 v218, 0xbdd2d3e7, v214
	v_fmaak_f32 v218, v214, v218, 0xc0135761
	v_mul_f32_e32 v218, v214, v218
	v_exp_f32_e32 v220, v218
	v_pk_mul_f32 v[218:219], v[30:31], v[186:187]
	v_mul_f32_e32 v221, 0xbdd2d3e7, v215
	v_fmaak_f32 v221, v215, v221, 0xc0135761
	v_mul_f32_e32 v222, 0xbdd2d3e7, v218
	v_mul_f32_e32 v221, v215, v221
	v_fmaak_f32 v222, v218, v222, 0xc0135761
; DI float gelu_tanh(float x) { const float t = x * (1.5957691216f + 0.0713548163f * x * x); return x * __builtin_amdgcn_rcpf(1.f + __builtin_amdgcn_exp2f(-1.4426950409f * t)); }
; #define ROWS8 _Pragma("unroll") for (int ai = 0; ai < 2; ++ai) _Pragma("unroll") for (int m = 0; m < 4; ++m) if (ai == 0 || !hf)
; #define PK8(v0, v1) ({ const u32x2 h0_ = pk4(v0), h1_ = pk4(v1); (u32x4){h0_.x, h0_.y, h1_.x, h1_.y}; })
;     DI void operator()(const Acc& acc, const Unit& u, int wr, int wc, int fr, int fq) const {
;     ...
;                     ROWS8 { const int r = row0 + ai * HALF + m * 16; f32x4 v0 = acc[ai][bj][m][0] * rsc[bj][0], v1 = acc[ai][bj][m][1] * rsc[bj][1];
;                         v0[0] = gelu_tanh(v0[0]); v0[1] = gelu_tanh(v0[1]); v0[2] = gelu_tanh(v0[2]); v0[3] = gelu_tanh(v0[3]);
;                         v1[0] = gelu_tanh(v1[0]); v1[1] = gelu_tanh(v1[1]); v1[2] = gelu_tanh(v1[2]); v1[3] = gelu_tanh(v1[3]);
;                         sq0 += v0 * v0; sq1 += v1 * v1; *(u32x4*)(WSB(OFF_VT) + (size_t)r * 8192 + cc) = PK8(v0, v1); }
; #pragma unroll
;                     for (int j = 0; j < 8; ++j) { float t = j < 4 ? sq0[j & 3] : sq1[j & 3];
;                         t += __shfl_xor(t, 1); t += __shfl_xor(t, 2); t += __shfl_xor(t, 4); t += __shfl_xor(t, 8);
;                         if (fr == 0) unsafeAtomicAdd(ssqv + cc + j, t); }
	v_mul_f32_e32 v222, v218, v222
	v_exp_f32_e32 v221, v221
	v_exp_f32_e32 v222, v222
	v_add_f32_e32 v220, 1.0, v220
	v_rcp_f32_e32 v240, v220
	v_add_f32_e32 v220, 1.0, v221
	v_rcp_f32_e32 v241, v220
	v_add_f32_e32 v220, 1.0, v222
	v_mul_f32_e32 v222, 0xbdd2d3e7, v238
	v_fmaak_f32 v222, v238, v222, 0xc0135761
	v_mul_f32_e32 v222, v238, v222
	v_exp_f32_e32 v222, v222
	v_pk_mul_f32 v[236:237], v[26:27], v[184:185]
	v_mul_f32_e32 v221, 0xbdd2d3e7, v219
	v_mul_f32_e32 v243, 0xbdd2d3e7, v236
	v_add_f32_e32 v222, 1.0, v222
	v_rcp_f32_e32 v242, v222
	v_mul_f32_e32 v222, 0xbdd2d3e7, v239
	v_fmaak_f32 v243, v236, v243, 0xc0135761
	v_mul_f32_e32 v244, 0xbdd2d3e7, v237
	v_fmaak_f32 v221, v219, v221, 0xc0135761
	v_fmaak_f32 v222, v239, v222, 0xc0135761
	v_mul_f32_e32 v243, v236, v243
	v_fmaak_f32 v244, v237, v244, 0xc0135761
	v_mul_f32_e32 v221, v219, v221
	v_mul_f32_e32 v222, v239, v222
	v_mul_f32_e32 v244, v237, v244
	v_exp_f32_e32 v243, v243
	v_exp_f32_e32 v221, v221
	v_exp_f32_e32 v222, v222
	v_exp_f32_e32 v245, v244
	v_add_f32_e32 v243, 1.0, v243
	v_add_f32_e32 v221, 1.0, v221
	v_add_f32_e32 v222, 1.0, v222
	v_rcp_f32_e32 v244, v243
	v_add_f32_e32 v243, 1.0, v245
	v_rcp_f32_e32 v220, v220
	v_rcp_f32_e32 v221, v221
	v_rcp_f32_e32 v245, v243
	v_rcp_f32_e32 v243, v222
	v_pk_mul_f32 v[240:241], v[214:215], v[240:241]
	v_pk_mul_f32 v[220:221], v[218:219], v[220:221]
	v_pk_mul_f32 v[214:215], v[236:237], v[244:245]
	v_pk_mul_f32 v[218:219], v[238:239], v[242:243]
	v_pk_fma_f32 v[238:239], v[240:241], v[240:241], v[234:235]
	v_cvt_pk_bf16_f32 v234, v240, v241
	v_add_co_u32_e32 v240, vcc, s71, v138
	v_pk_mul_f32 v[190:191], v[12:13], v[190:191]
	v_cvt_pk_bf16_f32 v235, v220, v221
	v_cvt_pk_bf16_f32 v236, v218, v219
	v_cvt_pk_bf16_f32 v237, v214, v215
	v_addc_co_u32_e32 v241, vcc, 0, v139, vcc
	v_mul_f32_e32 v222, 0xbdd2d3e7, v190
	global_store_dwordx4 v[240:241], v[234:237], off
	v_fmaak_f32 v222, v190, v222, 0xc0135761
	v_mul_f32_e32 v222, v190, v222
	v_mul_f32_e32 v234, 0xbdd2d3e7, v191
	v_fmaak_f32 v234, v191, v234, 0xc0135761
	v_mul_f32_e32 v234, v191, v234
	v_exp_f32_e32 v222, v222
	v_exp_f32_e32 v235, v234
	v_pk_mul_f32 v[186:187], v[14:15], v[186:187]
	v_add_f32_e32 v222, 1.0, v222
	v_rcp_f32_e32 v234, v222
	v_add_f32_e32 v222, 1.0, v235
	v_mul_f32_e32 v235, 0xbdd2d3e7, v186
	v_fmaak_f32 v235, v186, v235, 0xc0135761
	v_mul_f32_e32 v235, v186, v235
	v_exp_f32_e32 v236, v235
	v_mul_f32_e32 v235, 0xbdd2d3e7, v187
	v_fmaak_f32 v235, v187, v235, 0xc0135761
	v_mul_f32_e32 v235, v187, v235
	v_exp_f32_e32 v237, v235
	v_rcp_f32_e32 v235, v222
	v_pk_mul_f32 v[240:241], v[8:9], v[182:183]
	v_pk_mul_f32 v[184:185], v[10:11], v[184:185]
	v_mul_f32_e32 v182, 0xbdd2d3e7, v240
	v_pk_mul_f32 v[234:235], v[190:191], v[234:235]
	v_fmaak_f32 v182, v240, v182, 0xc0135761
	v_mul_f32_e32 v190, 0xbdd2d3e7, v184
	v_mul_f32_e32 v182, v240, v182
	v_fmaak_f32 v190, v184, v190, 0xc0135761
	v_add_f32_e32 v222, 1.0, v236
	v_mul_f32_e32 v190, v184, v190
	v_rcp_f32_e32 v236, v222
	v_add_f32_e32 v222, 1.0, v237
	v_exp_f32_e32 v182, v182
	v_rcp_f32_e32 v237, v222
	v_exp_f32_e32 v190, v190
	v_mul_f32_e32 v183, 0xbdd2d3e7, v241
	v_fmaak_f32 v183, v241, v183, 0xc0135761
	v_add_f32_e32 v182, 1.0, v182
	v_pk_mul_f32 v[186:187], v[186:187], v[236:237]
	v_mul_f32_e32 v183, v241, v183
	v_rcp_f32_e32 v236, v182
	v_add_f32_e32 v182, 1.0, v190
	v_pk_fma_f32 v[190:191], v[234:235], v[234:235], v[238:239]
	ds_bpermute_b32 v238, v226, v190
	v_exp_f32_e32 v183, v183
	v_rcp_f32_e32 v182, v182
	v_add_f32_e32 v222, 1.0, v183
	v_mul_f32_e32 v183, 0xbdd2d3e7, v185
	s_waitcnt lgkmcnt(0)
	v_add_f32_e32 v190, v190, v238
	v_fmaak_f32 v183, v185, v183, 0xc0135761
	v_rcp_f32_e32 v237, v222
	ds_bpermute_b32 v222, v227, v190
	v_mul_f32_e32 v183, v185, v183
	v_exp_f32_e32 v183, v183
	s_waitcnt lgkmcnt(0)
	v_add_f32_e32 v190, v190, v222
	ds_bpermute_b32 v222, v228, v190
	v_add_f32_e32 v183, 1.0, v183
	v_rcp_f32_e32 v183, v183
	s_waitcnt lgkmcnt(0)
	v_add_f32_e32 v190, v190, v222
	v_pk_mul_f32 v[182:183], v[184:185], v[182:183]
	v_pk_mul_f32 v[184:185], v[240:241], v[236:237]
	v_cvt_pk_bf16_f32 v236, v234, v235
	ds_bpermute_b32 v234, v229, v190
	v_add_co_u32_e32 v240, vcc, 0x2c0000, v138
	v_cvt_pk_bf16_f32 v237, v186, v187
	v_cvt_pk_bf16_f32 v238, v184, v185
	v_cvt_pk_bf16_f32 v239, v182, v183
	v_addc_co_u32_e32 v241, vcc, 0, v139, vcc
	global_store_dwordx4 v[240:241], v[236:239], off
	s_and_saveexec_b64 s[4:5], s[2:3]
	s_cbranch_execz .LBB0_331
	s_waitcnt lgkmcnt(0)
	v_add_f32_e32 v190, v190, v234
	global_atomic_add_f32 v[136:137], v190, off

; DI float gelu_tanh(float x) { const float t = x * (1.5957691216f + 0.0713548163f * x * x); return x * __builtin_amdgcn_rcpf(1.f + __builtin_amdgcn_exp2f(-1.4426950409f * t)); }
; #define ROWS8 _Pragma("unroll") for (int ai = 0; ai < 2; ++ai) _Pragma("unroll") for (int m = 0; m < 4; ++m) if (ai == 0 || !hf)
; #define PK8(v0, v1) ({ const u32x2 h0_ = pk4(v0), h1_ = pk4(v1); (u32x4){h0_.x, h0_.y, h1_.x, h1_.y}; })
;     DI void operator()(const Acc& acc, const Unit& u, int wr, int wc, int fr, int fq) const {
;     ...
;                 for (int bj = 0; bj < 2; ++bj) { const int cc = colp + bj * HALF;
;                     f32x4 sq0 = {0.f, 0.f, 0.f, 0.f}, sq1 = {0.f, 0.f, 0.f, 0.f};
;                     ROWS8 { const int r = row0 + ai * HALF + m * 16; f32x4 v0 = acc[ai][bj][m][0] * rsc[bj][0], v1 = acc[ai][bj][m][1] * rsc[bj][1];
;                         v0[0] = gelu_tanh(v0[0]); v0[1] = gelu_tanh(v0[1]); v0[2] = gelu_tanh(v0[2]); v0[3] = gelu_tanh(v0[3]);
;                         v1[0] = gelu_tanh(v1[0]); v1[1] = gelu_tanh(v1[1]); v1[2] = gelu_tanh(v1[2]); v1[3] = gelu_tanh(v1[3]);
;                         sq0 += v0 * v0; sq1 += v1 * v1; *(u32x4*)(WSB(OFF_VT) + (size_t)r * 8192 + cc) = PK8(v0, v1); }
.LBB0_345:
	s_or_b64 exec, exec, s[4:5]
	v_fmamk_f32 v132, v132, 0x3a000000, v233
	v_rsq_f32_e32 v176, v132
	v_fmamk_f32 v132, v133, 0x3a000000, v233
	v_rsq_f32_e32 v177, v132
	v_fmamk_f32 v128, v128, 0x3a000000, v233
	v_rsq_f32_e32 v174, v128
	v_fmamk_f32 v128, v129, 0x3a000000, v233
	v_rsq_f32_e32 v175, v128
	v_fmamk_f32 v128, v130, 0x3a000000, v233
	v_fmamk_f32 v132, v134, 0x3a000000, v233
	v_rsq_f32_e32 v182, v128
	v_fmamk_f32 v128, v131, 0x3a000000, v233
	v_rsq_f32_e32 v180, v132
	v_fmamk_f32 v132, v135, 0x3a000000, v233
	v_rsq_f32_e32 v183, v128
	v_pk_mul_f32 v[128:129], v[116:117], v[176:177]
	v_rsq_f32_e32 v181, v132
	v_mul_f32_e32 v130, 0xbdd2d3e7, v128
	v_fmaak_f32 v130, v128, v130, 0xc0135761
	v_mul_f32_e32 v130, v128, v130
	v_exp_f32_e32 v134, v130
	v_pk_mul_f32 v[130:131], v[118:119], v[180:181]
	v_mul_f32_e32 v135, 0xbdd2d3e7, v129
	v_fmaak_f32 v135, v129, v135, 0xc0135761
	v_mul_f32_e32 v188, 0xbdd2d3e7, v130
	v_mul_f32_e32 v135, v129, v135
	v_fmaak_f32 v188, v130, v188, 0xc0135761
	v_mul_f32_e32 v188, v130, v188
	v_exp_f32_e32 v135, v135
	v_exp_f32_e32 v190, v188
	v_add_f32_e32 v134, 1.0, v134
	v_pk_mul_f32 v[132:133], v[114:115], v[182:183]
	v_pk_mul_f32 v[184:185], v[112:113], v[174:175]
	v_rcp_f32_e32 v188, v134
	v_add_f32_e32 v134, 1.0, v135
	v_rcp_f32_e32 v189, v134
	v_add_f32_e32 v134, 1.0, v190
	v_mul_f32_e32 v135, 0xbdd2d3e7, v131
	v_mul_f32_e32 v190, 0xbdd2d3e7, v184
	v_mul_f32_e32 v191, 0xbdd2d3e7, v185
	v_mul_f32_e32 v194, 0xbdd2d3e7, v132
	v_mul_f32_e32 v195, 0xbdd2d3e7, v133
	v_fmaak_f32 v135, v131, v135, 0xc0135761
	v_fmaak_f32 v190, v184, v190, 0xc0135761
	v_fmaak_f32 v191, v185, v191, 0xc0135761
	v_fmaak_f32 v194, v132, v194, 0xc0135761
	v_fmaak_f32 v195, v133, v195, 0xc0135761
	v_mul_f32_e32 v135, v131, v135
	v_mul_f32_e32 v190, v184, v190
	v_mul_f32_e32 v191, v185, v191
	v_mul_f32_e32 v194, v132, v194
	v_mul_f32_e32 v195, v133, v195
	v_exp_f32_e32 v135, v135
	v_exp_f32_e32 v190, v190
	v_exp_f32_e32 v191, v191
	v_exp_f32_e32 v194, v194
	v_exp_f32_e32 v195, v195
	v_add_f32_e32 v135, 1.0, v135
	v_add_f32_e32 v190, 1.0, v190
	v_add_f32_e32 v191, 1.0, v191
	v_add_f32_e32 v194, 1.0, v194
	v_add_f32_e32 v195, 1.0, v195
	v_rcp_f32_e32 v134, v134
	v_rcp_f32_e32 v135, v135
	v_rcp_f32_e32 v190, v190
	v_rcp_f32_e32 v194, v194
	v_rcp_f32_e32 v195, v195
	v_rcp_f32_e32 v191, v191
	v_pk_mul_f32 v[134:135], v[130:131], v[134:135]
	v_pk_mul_f32 v[198:199], v[128:129], v[188:189]
	v_pk_mul_f32 v[128:129], v[132:133], v[194:195]
	v_pk_mul_f32 v[130:131], v[184:185], v[190:191]
	v_cvt_pk_bf16_f32 v188, v198, v199
	v_cvt_pk_bf16_f32 v189, v134, v135
	v_cvt_pk_bf16_f32 v190, v130, v131
	v_cvt_pk_bf16_f32 v191, v128, v129
	v_pk_mul_f32 v[132:133], v[100:101], v[176:177]
	v_lshl_add_u64 v[192:193], v[138:139], 0, s[24:25]
	v_lshl_add_u64 v[186:187], v[138:139], 0, s[26:27]
	v_lshl_add_u64 v[178:179], v[138:139], 0, s[28:29]
	s_waitcnt lgkmcnt(0)
	v_lshl_add_u64 v[172:173], v[138:139], 0, s[30:31]
	global_store_dwordx4 v[138:139], v[188:191], off offset:256
	v_mul_f32_e32 v138, 0xbdd2d3e7, v132
	v_fmaak_f32 v138, v132, v138, 0xc0135761
	v_mul_f32_e32 v138, v132, v138
	v_exp_f32_e32 v184, v138
	v_pk_mul_f32 v[138:139], v[102:103], v[180:181]
	v_mul_f32_e32 v185, 0xbdd2d3e7, v133
	v_fmaak_f32 v185, v133, v185, 0xc0135761
	v_mul_f32_e32 v194, 0xbdd2d3e7, v138
	v_mul_f32_e32 v185, v133, v185
	v_fmaak_f32 v194, v138, v194, 0xc0135761
	v_mul_f32_e32 v194, v138, v194
	v_exp_f32_e32 v185, v185
	v_exp_f32_e32 v196, v194
	v_add_f32_e32 v184, 1.0, v184
	v_pk_mul_f32 v[188:189], v[98:99], v[182:183]
	v_pk_mul_f32 v[190:191], v[96:97], v[174:175]
	v_rcp_f32_e32 v194, v184
	v_add_f32_e32 v184, 1.0, v185
	v_rcp_f32_e32 v195, v184
	v_add_f32_e32 v184, 1.0, v196
	v_mul_f32_e32 v185, 0xbdd2d3e7, v139
	v_mul_f32_e32 v196, 0xbdd2d3e7, v190
	v_mul_f32_e32 v197, 0xbdd2d3e7, v191
	v_mul_f32_e32 v200, 0xbdd2d3e7, v188
	v_mul_f32_e32 v201, 0xbdd2d3e7, v189
	v_fmaak_f32 v185, v139, v185, 0xc0135761
	v_fmaak_f32 v196, v190, v196, 0xc0135761
	v_fmaak_f32 v197, v191, v197, 0xc0135761
	v_fmaak_f32 v200, v188, v200, 0xc0135761
	v_fmaak_f32 v201, v189, v201, 0xc0135761
	v_mul_f32_e32 v185, v139, v185
	v_mul_f32_e32 v196, v190, v196
	v_mul_f32_e32 v197, v191, v197
	v_mul_f32_e32 v200, v188, v200
	v_mul_f32_e32 v201, v189, v201
	v_exp_f32_e32 v185, v185
	v_exp_f32_e32 v196, v196
	v_exp_f32_e32 v197, v197
	v_exp_f32_e32 v200, v200
	v_exp_f32_e32 v201, v201
	v_add_f32_e32 v185, 1.0, v185
	v_add_f32_e32 v196, 1.0, v196
	v_add_f32_e32 v197, 1.0, v197
	v_add_f32_e32 v200, 1.0, v200
	v_add_f32_e32 v201, 1.0, v201
	v_rcp_f32_e32 v184, v184
	v_rcp_f32_e32 v185, v185
	v_rcp_f32_e32 v196, v196
	v_rcp_f32_e32 v200, v200
	v_rcp_f32_e32 v201, v201
	v_rcp_f32_e32 v197, v197
	v_pk_mul_f32 v[184:185], v[138:139], v[184:185]
	v_pk_mul_f32 v[204:205], v[132:133], v[194:195]
	v_pk_mul_f32 v[132:133], v[188:189], v[200:201]
	v_pk_mul_f32 v[138:139], v[190:191], v[196:197]
	v_cvt_pk_bf16_f32 v188, v204, v205
	v_cvt_pk_bf16_f32 v189, v184, v185
	v_cvt_pk_bf16_f32 v190, v138, v139
	v_cvt_pk_bf16_f32 v191, v132, v133
	global_store_dwordx4 v[166:167], v[188:191], off offset:256
	v_pk_mul_f32 v[166:167], v[84:85], v[176:177]
	v_pk_mul_f32 v[194:195], v[82:83], v[182:183]
	v_mul_f32_e32 v188, 0xbdd2d3e7, v166
	v_fmaak_f32 v188, v166, v188, 0xc0135761
	v_mul_f32_e32 v188, v166, v188
	v_exp_f32_e32 v190, v188
	v_pk_mul_f32 v[188:189], v[86:87], v[180:181]
	v_mul_f32_e32 v191, 0xbdd2d3e7, v167
	v_fmaak_f32 v191, v167, v191, 0xc0135761
	v_mul_f32_e32 v200, 0xbdd2d3e7, v188
	v_mul_f32_e32 v191, v167, v191
	v_fmaak_f32 v200, v188, v200, 0xc0135761
	v_mul_f32_e32 v200, v188, v200
; DI float gelu_tanh(float x) { const float t = x * (1.5957691216f + 0.0713548163f * x * x); return x * __builtin_amdgcn_rcpf(1.f + __builtin_amdgcn_exp2f(-1.4426950409f * t)); }
; #define ROWS8 _Pragma("unroll") for (int ai = 0; ai < 2; ++ai) _Pragma("unroll") for (int m = 0; m < 4; ++m) if (ai == 0 || !hf)
; #define PK8(v0, v1) ({ const u32x2 h0_ = pk4(v0), h1_ = pk4(v1); (u32x4){h0_.x, h0_.y, h1_.x, h1_.y}; })
;     DI void operator()(const Acc& acc, const Unit& u, int wr, int wc, int fr, int fq) const {
;     ...
;                     ROWS8 { const int r = row0 + ai * HALF + m * 16; f32x4 v0 = acc[ai][bj][m][0] * rsc[bj][0], v1 = acc[ai][bj][m][1] * rsc[bj][1];
;                         v0[0] = gelu_tanh(v0[0]); v0[1] = gelu_tanh(v0[1]); v0[2] = gelu_tanh(v0[2]); v0[3] = gelu_tanh(v0[3]);
;                         v1[0] = gelu_tanh(v1[0]); v1[1] = gelu_tanh(v1[1]); v1[2] = gelu_tanh(v1[2]); v1[3] = gelu_tanh(v1[3]);
;                         sq0 += v0 * v0; sq1 += v1 * v1; *(u32x4*)(WSB(OFF_VT) + (size_t)r * 8192 + cc) = PK8(v0, v1); }
	v_exp_f32_e32 v191, v191
	v_exp_f32_e32 v202, v200
	v_add_f32_e32 v190, 1.0, v190
	v_pk_mul_f32 v[196:197], v[80:81], v[174:175]
	v_rcp_f32_e32 v200, v190
	v_add_f32_e32 v190, 1.0, v191
	v_rcp_f32_e32 v201, v190
	v_add_f32_e32 v190, 1.0, v202
	v_mul_f32_e32 v191, 0xbdd2d3e7, v189
	v_mul_f32_e32 v202, 0xbdd2d3e7, v196
	v_mul_f32_e32 v203, 0xbdd2d3e7, v197
	v_mul_f32_e32 v206, 0xbdd2d3e7, v194
	v_mul_f32_e32 v207, 0xbdd2d3e7, v195
	v_fmaak_f32 v191, v189, v191, 0xc0135761
	v_fmaak_f32 v202, v196, v202, 0xc0135761
	v_fmaak_f32 v203, v197, v203, 0xc0135761
	v_fmaak_f32 v206, v194, v206, 0xc0135761
	v_fmaak_f32 v207, v195, v207, 0xc0135761
	v_mul_f32_e32 v191, v189, v191
	v_mul_f32_e32 v202, v196, v202
	v_mul_f32_e32 v203, v197, v203
	v_mul_f32_e32 v206, v194, v206
	v_mul_f32_e32 v207, v195, v207
	v_exp_f32_e32 v191, v191
	v_exp_f32_e32 v202, v202
	v_exp_f32_e32 v203, v203
	v_exp_f32_e32 v206, v206
	v_exp_f32_e32 v207, v207
	v_add_f32_e32 v191, 1.0, v191
	v_add_f32_e32 v202, 1.0, v202
	v_add_f32_e32 v203, 1.0, v203
	v_add_f32_e32 v206, 1.0, v206
	v_add_f32_e32 v207, 1.0, v207
	v_rcp_f32_e32 v190, v190
	v_rcp_f32_e32 v191, v191
	v_rcp_f32_e32 v202, v202
	v_rcp_f32_e32 v206, v206
	v_rcp_f32_e32 v207, v207
	v_rcp_f32_e32 v203, v203
	v_pk_mul_f32 v[190:191], v[188:189], v[190:191]
	v_pk_mul_f32 v[208:209], v[166:167], v[200:201]
	v_pk_mul_f32 v[166:167], v[194:195], v[206:207]
	v_pk_mul_f32 v[188:189], v[196:197], v[202:203]
	v_cvt_pk_bf16_f32 v194, v208, v209
	v_cvt_pk_bf16_f32 v195, v190, v191
	v_cvt_pk_bf16_f32 v196, v188, v189
	v_cvt_pk_bf16_f32 v197, v166, v167
	global_store_dwordx4 v[168:169], v[194:197], off offset:256
	v_pk_mul_f32 v[168:169], v[68:69], v[176:177]
	v_pk_mul_f32 v[200:201], v[66:67], v[182:183]
	v_mul_f32_e32 v194, 0xbdd2d3e7, v168
	v_fmaak_f32 v194, v168, v194, 0xc0135761
	v_mul_f32_e32 v194, v168, v194
	v_exp_f32_e32 v196, v194
	v_pk_mul_f32 v[194:195], v[70:71], v[180:181]
	v_mul_f32_e32 v197, 0xbdd2d3e7, v169
	v_fmaak_f32 v197, v169, v197, 0xc0135761
	v_mul_f32_e32 v206, 0xbdd2d3e7, v194
	v_mul_f32_e32 v197, v169, v197
	v_fmaak_f32 v206, v194, v206, 0xc0135761
	v_mul_f32_e32 v206, v194, v206
	v_exp_f32_e32 v197, v197
	v_exp_f32_e32 v210, v206
	v_add_f32_e32 v196, 1.0, v196
	v_pk_mul_f32 v[202:203], v[64:65], v[174:175]
	v_rcp_f32_e32 v206, v196
	v_add_f32_e32 v196, 1.0, v197
	v_rcp_f32_e32 v207, v196
	v_add_f32_e32 v196, 1.0, v210
	v_mul_f32_e32 v197, 0xbdd2d3e7, v195
	v_mul_f32_e32 v210, 0xbdd2d3e7, v202
	v_mul_f32_e32 v211, 0xbdd2d3e7, v203
	v_mul_f32_e32 v212, 0xbdd2d3e7, v200
	v_mul_f32_e32 v213, 0xbdd2d3e7, v201
	v_fmaak_f32 v197, v195, v197, 0xc0135761
	v_fmaak_f32 v210, v202, v210, 0xc0135761
	v_fmaak_f32 v211, v203, v211, 0xc0135761
	v_fmaak_f32 v212, v200, v212, 0xc0135761
	v_fmaak_f32 v213, v201, v213, 0xc0135761
	v_mul_f32_e32 v197, v195, v197
	v_mul_f32_e32 v210, v202, v210
	v_mul_f32_e32 v211, v203, v211
	v_mul_f32_e32 v212, v200, v212
	v_mul_f32_e32 v213, v201, v213
	v_exp_f32_e32 v197, v197
	v_exp_f32_e32 v210, v210
	v_exp_f32_e32 v211, v211
	v_exp_f32_e32 v212, v212
	v_exp_f32_e32 v213, v213
	v_add_f32_e32 v197, 1.0, v197
	v_add_f32_e32 v210, 1.0, v210
	v_add_f32_e32 v211, 1.0, v211
	v_add_f32_e32 v212, 1.0, v212
	v_add_f32_e32 v213, 1.0, v213
	v_rcp_f32_e32 v196, v196
	v_rcp_f32_e32 v197, v197
	v_rcp_f32_e32 v210, v210
	v_rcp_f32_e32 v212, v212
	v_rcp_f32_e32 v213, v213
	v_rcp_f32_e32 v211, v211
	v_pk_mul_f32 v[196:197], v[194:195], v[196:197]
	v_pk_mul_f32 v[206:207], v[168:169], v[206:207]
	v_pk_mul_f32 v[168:169], v[200:201], v[212:213]
	v_pk_mul_f32 v[194:195], v[202:203], v[210:211]
	v_cvt_pk_bf16_f32 v200, v206, v207
	v_cvt_pk_bf16_f32 v201, v196, v197
	v_cvt_pk_bf16_f32 v202, v194, v195
	v_cvt_pk_bf16_f32 v203, v168, v169
	global_store_dwordx4 v[170:171], v[200:203], off offset:256
	v_pk_mul_f32 v[170:171], v[204:205], v[204:205]
	v_pk_mul_f32 v[204:205], v[50:51], v[182:183]
	v_pk_fma_f32 v[170:171], v[198:199], v[198:199], v[170:171]
	v_mul_f32_e32 v212, 0xbdd2d3e7, v204
	v_pk_fma_f32 v[170:171], v[208:209], v[208:209], v[170:171]
	v_mul_f32_e32 v213, 0xbdd2d3e7, v205
	v_pk_fma_f32 v[202:203], v[206:207], v[206:207], v[170:171]
	v_pk_mul_f32 v[170:171], v[52:53], v[176:177]
	v_pk_mul_f32 v[206:207], v[48:49], v[174:175]
	v_mul_f32_e32 v198, 0xbdd2d3e7, v170
	v_fmaak_f32 v198, v170, v198, 0xc0135761
	v_mul_f32_e32 v198, v170, v198
	v_exp_f32_e32 v200, v198
	v_pk_mul_f32 v[198:199], v[54:55], v[180:181]
	v_mul_f32_e32 v201, 0xbdd2d3e7, v171
	v_fmaak_f32 v201, v171, v201, 0xc0135761
	v_mul_f32_e32 v208, 0xbdd2d3e7, v198
	v_mul_f32_e32 v201, v171, v201
	v_fmaak_f32 v208, v198, v208, 0xc0135761
	v_mul_f32_e32 v208, v198, v208
	v_exp_f32_e32 v201, v201
	v_exp_f32_e32 v210, v208
	v_add_f32_e32 v200, 1.0, v200
	v_rcp_f32_e32 v208, v200
	v_add_f32_e32 v200, 1.0, v201
	v_rcp_f32_e32 v209, v200
	v_add_f32_e32 v200, 1.0, v210
	v_mul_f32_e32 v201, 0xbdd2d3e7, v199
	v_mul_f32_e32 v210, 0xbdd2d3e7, v206
	v_mul_f32_e32 v211, 0xbdd2d3e7, v207
	v_fmaak_f32 v201, v199, v201, 0xc0135761
	v_fmaak_f32 v210, v206, v210, 0xc0135761
	v_fmaak_f32 v211, v207, v211, 0xc0135761
	v_fmaak_f32 v212, v204, v212, 0xc0135761
	v_fmaak_f32 v213, v205, v213, 0xc0135761
	v_mul_f32_e32 v201, v199, v201
	v_mul_f32_e32 v210, v206, v210
	v_mul_f32_e32 v211, v207, v211
	v_mul_f32_e32 v212, v204, v212
	v_mul_f32_e32 v213, v205, v213
	v_exp_f32_e32 v201, v201
	v_exp_f32_e32 v210, v210
	v_exp_f32_e32 v211, v211
	v_exp_f32_e32 v212, v212
	v_exp_f32_e32 v213, v213
	v_add_f32_e32 v201, 1.0, v201
	v_add_f32_e32 v210, 1.0, v210
	v_add_f32_e32 v211, 1.0, v211
	v_add_f32_e32 v212, 1.0, v212
	v_add_f32_e32 v213, 1.0, v213
	v_rcp_f32_e32 v200, v200
; DI float gelu_tanh(float x) { const float t = x * (1.5957691216f + 0.0713548163f * x * x); return x * __builtin_amdgcn_rcpf(1.f + __builtin_amdgcn_exp2f(-1.4426950409f * t)); }
; #define ROWS8 _Pragma("unroll") for (int ai = 0; ai < 2; ++ai) _Pragma("unroll") for (int m = 0; m < 4; ++m) if (ai == 0 || !hf)
; #define PK8(v0, v1) ({ const u32x2 h0_ = pk4(v0), h1_ = pk4(v1); (u32x4){h0_.x, h0_.y, h1_.x, h1_.y}; })
;     DI void operator()(const Acc& acc, const Unit& u, int wr, int wc, int fr, int fq) const {
;     ...
;                     ROWS8 { const int r = row0 + ai * HALF + m * 16; f32x4 v0 = acc[ai][bj][m][0] * rsc[bj][0], v1 = acc[ai][bj][m][1] * rsc[bj][1];
;                         v0[0] = gelu_tanh(v0[0]); v0[1] = gelu_tanh(v0[1]); v0[2] = gelu_tanh(v0[2]); v0[3] = gelu_tanh(v0[3]);
;                         v1[0] = gelu_tanh(v1[0]); v1[1] = gelu_tanh(v1[1]); v1[2] = gelu_tanh(v1[2]); v1[3] = gelu_tanh(v1[3]);
;                         sq0 += v0 * v0; sq1 += v1 * v1; *(u32x4*)(WSB(OFF_VT) + (size_t)r * 8192 + cc) = PK8(v0, v1); }
	v_rcp_f32_e32 v201, v201
	v_rcp_f32_e32 v210, v210
	v_rcp_f32_e32 v212, v212
	v_rcp_f32_e32 v213, v213
	v_rcp_f32_e32 v211, v211
	v_pk_mul_f32 v[200:201], v[198:199], v[200:201]
	v_pk_mul_f32 v[208:209], v[170:171], v[208:209]
	v_pk_mul_f32 v[170:171], v[204:205], v[212:213]
	v_pk_mul_f32 v[198:199], v[206:207], v[210:211]
	v_pk_fma_f32 v[206:207], v[208:209], v[208:209], v[202:203]
	v_cvt_pk_bf16_f32 v202, v208, v209
	v_cvt_pk_bf16_f32 v203, v200, v201
	v_cvt_pk_bf16_f32 v204, v198, v199
	v_cvt_pk_bf16_f32 v205, v170, v171
	global_store_dwordx4 v[192:193], v[202:205], off offset:256
	v_pk_mul_f32 v[192:193], v[36:37], v[176:177]
	v_pk_mul_f32 v[208:209], v[34:35], v[182:183]
	v_mul_f32_e32 v202, 0xbdd2d3e7, v192
	v_fmaak_f32 v202, v192, v202, 0xc0135761
	v_mul_f32_e32 v202, v192, v202
	v_exp_f32_e32 v204, v202
	v_pk_mul_f32 v[202:203], v[38:39], v[180:181]
	v_pk_mul_f32 v[210:211], v[32:33], v[174:175]
	v_mul_f32_e32 v205, 0xbdd2d3e7, v193
	v_mul_f32_e32 v212, 0xbdd2d3e7, v202
	v_mul_f32_e32 v213, 0xbdd2d3e7, v203
	v_mul_f32_e32 v214, 0xbdd2d3e7, v210
	v_mul_f32_e32 v215, 0xbdd2d3e7, v211
	v_mul_f32_e32 v216, 0xbdd2d3e7, v208
	v_mul_f32_e32 v217, 0xbdd2d3e7, v209
	v_fmaak_f32 v205, v193, v205, 0xc0135761
	v_fmaak_f32 v212, v202, v212, 0xc0135761
	v_fmaak_f32 v213, v203, v213, 0xc0135761
	v_fmaak_f32 v214, v210, v214, 0xc0135761
	v_fmaak_f32 v215, v211, v215, 0xc0135761
	v_fmaak_f32 v216, v208, v216, 0xc0135761
	v_fmaak_f32 v217, v209, v217, 0xc0135761
	v_mul_f32_e32 v205, v193, v205
	v_mul_f32_e32 v212, v202, v212
	v_mul_f32_e32 v213, v203, v213
	v_mul_f32_e32 v214, v210, v214
	v_mul_f32_e32 v215, v211, v215
	v_mul_f32_e32 v216, v208, v216
	v_mul_f32_e32 v217, v209, v217
	v_exp_f32_e32 v205, v205
	v_exp_f32_e32 v212, v212
	v_exp_f32_e32 v213, v213
	v_exp_f32_e32 v214, v214
	v_exp_f32_e32 v215, v215
	v_exp_f32_e32 v216, v216
	v_exp_f32_e32 v217, v217
	v_add_f32_e32 v204, 1.0, v204
	v_add_f32_e32 v205, 1.0, v205
	v_add_f32_e32 v212, 1.0, v212
	v_add_f32_e32 v213, 1.0, v213
	v_add_f32_e32 v214, 1.0, v214
	v_add_f32_e32 v215, 1.0, v215
	v_add_f32_e32 v216, 1.0, v216
	v_add_f32_e32 v217, 1.0, v217
	v_rcp_f32_e32 v204, v204
	v_rcp_f32_e32 v205, v205
	v_rcp_f32_e32 v212, v212
	v_rcp_f32_e32 v213, v213
	v_rcp_f32_e32 v214, v214
	v_rcp_f32_e32 v216, v216
	v_rcp_f32_e32 v217, v217
	v_rcp_f32_e32 v215, v215
	v_pk_mul_f32 v[218:219], v[192:193], v[204:205]
	v_pk_mul_f32 v[204:205], v[202:203], v[212:213]
	v_pk_mul_f32 v[192:193], v[208:209], v[216:217]
	v_pk_mul_f32 v[202:203], v[210:211], v[214:215]
	v_pk_fma_f32 v[210:211], v[218:219], v[218:219], v[206:207]
	v_cvt_pk_bf16_f32 v206, v218, v219
	v_cvt_pk_bf16_f32 v207, v204, v205
	v_cvt_pk_bf16_f32 v208, v202, v203
	v_cvt_pk_bf16_f32 v209, v192, v193
	global_store_dwordx4 v[186:187], v[206:209], off offset:256
	v_pk_mul_f32 v[186:187], v[20:21], v[176:177]
	v_pk_mul_f32 v[212:213], v[18:19], v[182:183]
	v_mul_f32_e32 v206, 0xbdd2d3e7, v186
	v_fmaak_f32 v206, v186, v206, 0xc0135761
	v_mul_f32_e32 v206, v186, v206
	v_exp_f32_e32 v208, v206
	v_pk_mul_f32 v[206:207], v[22:23], v[180:181]
	v_mul_f32_e32 v209, 0xbdd2d3e7, v187
	v_fmaak_f32 v209, v187, v209, 0xc0135761
	v_mul_f32_e32 v216, 0xbdd2d3e7, v206
	v_mul_f32_e32 v209, v187, v209
	v_fmaak_f32 v216, v206, v216, 0xc0135761
	v_mul_f32_e32 v216, v206, v216
	v_exp_f32_e32 v209, v209
	v_exp_f32_e32 v218, v216
	v_add_f32_e32 v208, 1.0, v208
	v_pk_mul_f32 v[214:215], v[16:17], v[174:175]
	v_rcp_f32_e32 v216, v208
	v_add_f32_e32 v208, 1.0, v209
	v_rcp_f32_e32 v217, v208
	v_add_f32_e32 v208, 1.0, v218
	v_mul_f32_e32 v209, 0xbdd2d3e7, v207
	v_mul_f32_e32 v218, 0xbdd2d3e7, v214
	v_mul_f32_e32 v219, 0xbdd2d3e7, v215
	v_mul_f32_e32 v220, 0xbdd2d3e7, v212
	v_mul_f32_e32 v221, 0xbdd2d3e7, v213
	v_fmaak_f32 v209, v207, v209, 0xc0135761
	v_fmaak_f32 v218, v214, v218, 0xc0135761
	v_fmaak_f32 v219, v215, v219, 0xc0135761
	v_fmaak_f32 v220, v212, v220, 0xc0135761
	v_fmaak_f32 v221, v213, v221, 0xc0135761
	v_mul_f32_e32 v209, v207, v209
	v_mul_f32_e32 v218, v214, v218
	v_mul_f32_e32 v219, v215, v219
	v_mul_f32_e32 v220, v212, v220
	v_mul_f32_e32 v221, v213, v221
	v_exp_f32_e32 v209, v209
	v_exp_f32_e32 v218, v218
	v_exp_f32_e32 v219, v219
	v_exp_f32_e32 v220, v220
	v_exp_f32_e32 v221, v221
	v_add_f32_e32 v209, 1.0, v209
	v_add_f32_e32 v218, 1.0, v218
	v_add_f32_e32 v219, 1.0, v219
	v_add_f32_e32 v220, 1.0, v220
	v_add_f32_e32 v221, 1.0, v221
	v_rcp_f32_e32 v208, v208
	v_rcp_f32_e32 v209, v209
	v_rcp_f32_e32 v218, v218
	v_rcp_f32_e32 v220, v220
	v_rcp_f32_e32 v221, v221
	v_rcp_f32_e32 v219, v219
	v_pk_mul_f32 v[208:209], v[206:207], v[208:209]
	v_pk_mul_f32 v[216:217], v[186:187], v[216:217]
	v_pk_mul_f32 v[186:187], v[212:213], v[220:221]
	v_pk_mul_f32 v[206:207], v[214:215], v[218:219]
	v_pk_fma_f32 v[214:215], v[216:217], v[216:217], v[210:211]
	v_cvt_pk_bf16_f32 v210, v216, v217
	v_cvt_pk_bf16_f32 v211, v208, v209
	v_cvt_pk_bf16_f32 v212, v206, v207
	v_cvt_pk_bf16_f32 v213, v186, v187
	v_pk_mul_f32 v[176:177], v[4:5], v[176:177]
	global_store_dwordx4 v[178:179], v[210:213], off offset:256
	v_mul_f32_e32 v178, 0xbdd2d3e7, v176
	v_fmaak_f32 v178, v176, v178, 0xc0135761
	v_mul_f32_e32 v179, 0xbdd2d3e7, v177
	v_mul_f32_e32 v178, v176, v178
	v_fmaak_f32 v179, v177, v179, 0xc0135761
	v_mul_f32_e32 v179, v177, v179
	v_exp_f32_e32 v178, v178
	v_exp_f32_e32 v179, v179
	v_pk_mul_f32 v[180:181], v[6:7], v[180:181]
	v_pk_mul_f32 v[210:211], v[0:1], v[174:175]
	v_add_f32_e32 v174, 1.0, v178
	v_mul_f32_e32 v178, 0xbdd2d3e7, v180
	v_add_f32_e32 v175, 1.0, v179
	v_fmaak_f32 v178, v180, v178, 0xc0135761
	v_mul_f32_e32 v179, 0xbdd2d3e7, v181
	v_mul_f32_e32 v178, v180, v178
	v_fmaak_f32 v179, v181, v179, 0xc0135761
	v_mul_f32_e32 v179, v181, v179
	v_exp_f32_e32 v178, v178
	v_exp_f32_e32 v179, v179
	v_rcp_f32_e32 v174, v174
	v_add_f32_e32 v178, 1.0, v178
	v_rcp_f32_e32 v212, v178
	v_add_f32_e32 v178, 1.0, v179
	v_rcp_f32_e32 v213, v178
	v_mul_f32_e32 v178, 0xbdd2d3e7, v210
	v_fmaak_f32 v178, v210, v178, 0xc0135761
	v_mul_f32_e32 v179, 0xbdd2d3e7, v211
	v_mul_f32_e32 v178, v210, v178
	v_fmaak_f32 v179, v211, v179, 0xc0135761
	v_mul_f32_e32 v179, v211, v179
	v_rcp_f32_e32 v175, v175
	v_exp_f32_e32 v178, v178
	v_exp_f32_e32 v179, v179
	v_pk_mul_f32 v[216:217], v[176:177], v[174:175]
	v_add_f32_e32 v174, 1.0, v178
	v_rcp_f32_e32 v176, v174
	v_add_f32_e32 v174, 1.0, v179
	v_pk_fma_f32 v[178:179], v[216:217], v[216:217], v[214:215]
	ds_bpermute_b32 v214, v226, v178
	v_pk_mul_f32 v[182:183], v[2:3], v[182:183]
	v_rcp_f32_e32 v177, v174
	v_mul_f32_e32 v174, 0xbdd2d3e7, v182
	v_mul_f32_e32 v175, 0xbdd2d3e7, v183
	s_waitcnt lgkmcnt(0)
; DI float gelu_tanh(float x) { const float t = x * (1.5957691216f + 0.0713548163f * x * x); return x * __builtin_amdgcn_rcpf(1.f + __builtin_amdgcn_exp2f(-1.4426950409f * t)); }
; #define ROWS8 _Pragma("unroll") for (int ai = 0; ai < 2; ++ai) _Pragma("unroll") for (int m = 0; m < 4; ++m) if (ai == 0 || !hf)
; #define PK8(v0, v1) ({ const u32x2 h0_ = pk4(v0), h1_ = pk4(v1); (u32x4){h0_.x, h0_.y, h1_.x, h1_.y}; })
;     DI void operator()(const Acc& acc, const Unit& u, int wr, int wc, int fr, int fq) const {
;     ...
;                     ROWS8 { const int r = row0 + ai * HALF + m * 16; f32x4 v0 = acc[ai][bj][m][0] * rsc[bj][0], v1 = acc[ai][bj][m][1] * rsc[bj][1];
;                         v0[0] = gelu_tanh(v0[0]); v0[1] = gelu_tanh(v0[1]); v0[2] = gelu_tanh(v0[2]); v0[3] = gelu_tanh(v0[3]);
;                         v1[0] = gelu_tanh(v1[0]); v1[1] = gelu_tanh(v1[1]); v1[2] = gelu_tanh(v1[2]); v1[3] = gelu_tanh(v1[3]);
;                         sq0 += v0 * v0; sq1 += v1 * v1; *(u32x4*)(WSB(OFF_VT) + (size_t)r * 8192 + cc) = PK8(v0, v1); }
; #pragma unroll
;                     for (int j = 0; j < 8; ++j) { float t = j < 4 ? sq0[j & 3] : sq1[j & 3];
;                         t += __shfl_xor(t, 1); t += __shfl_xor(t, 2); t += __shfl_xor(t, 4); t += __shfl_xor(t, 8);
;                         if (fr == 0) unsafeAtomicAdd(ssqv + cc + j, t); }
	v_add_f32_e32 v178, v178, v214
	v_fmaak_f32 v174, v182, v174, 0xc0135761
	v_fmaak_f32 v175, v183, v175, 0xc0135761
	ds_bpermute_b32 v214, v227, v178
	v_mul_f32_e32 v174, v182, v174
	v_mul_f32_e32 v175, v183, v175
	v_exp_f32_e32 v174, v174
	v_exp_f32_e32 v175, v175
	s_waitcnt lgkmcnt(0)
	v_add_f32_e32 v178, v178, v214
	ds_bpermute_b32 v214, v228, v178
	v_add_f32_e32 v174, 1.0, v174
	v_add_f32_e32 v175, 1.0, v175
	v_rcp_f32_e32 v174, v174
	v_rcp_f32_e32 v175, v175
	s_waitcnt lgkmcnt(0)
	v_add_f32_e32 v178, v178, v214
	v_pk_mul_f32 v[180:181], v[180:181], v[212:213]
	v_pk_mul_f32 v[176:177], v[210:211], v[176:177]
	v_pk_mul_f32 v[174:175], v[182:183], v[174:175]
	ds_bpermute_b32 v182, v229, v178
	v_cvt_pk_bf16_f32 v210, v216, v217
	v_cvt_pk_bf16_f32 v211, v180, v181
	v_cvt_pk_bf16_f32 v212, v176, v177
	v_cvt_pk_bf16_f32 v213, v174, v175
	global_store_dwordx4 v[172:173], v[210:213], off offset:256
	s_and_saveexec_b64 s[4:5], s[2:3]
	s_cbranch_execz .LBB0_347
	s_waitcnt lgkmcnt(0)
	v_add_f32_e32 v172, v178, v182
	global_atomic_add_f32 v[136:137], v172, off offset:512

; DI float gelu_tanh(float x) { const float t = x * (1.5957691216f + 0.0713548163f * x * x); return x * __builtin_amdgcn_rcpf(1.f + __builtin_amdgcn_exp2f(-1.4426950409f * t)); }
; #define ROWS8 _Pragma("unroll") for (int ai = 0; ai < 2; ++ai) _Pragma("unroll") for (int m = 0; m < 4; ++m) if (ai == 0 || !hf)
; #define PK8(v0, v1) ({ const u32x2 h0_ = pk4(v0), h1_ = pk4(v1); (u32x4){h0_.x, h0_.y, h1_.x, h1_.y}; })
;     DI void operator()(const Acc& acc, const Unit& u, int wr, int wc, int fr, int fq) const {
;     ...
;                 ROWS8 { const int r = row0 + ai * HALF + m * 16; const float rs = rsv[ai][m];
;                     if (u.pn < 4) { bf16_t* dst = WSB(OFF_U) + (size_t)r * 1024 + colp;
; #pragma unroll
;                         for (int bj = 0; bj < 2; ++bj) { f32x4 v0 = acc[ai][bj][m][0] * rs, v1 = acc[ai][bj][m][1] * rs;
;                             v0[0] = gelu_tanh(v0[0]); v0[1] = gelu_tanh(v0[1]); v0[2] = gelu_tanh(v0[2]); v0[3] = gelu_tanh(v0[3]);
;                             v1[0] = gelu_tanh(v1[0]); v1[1] = gelu_tanh(v1[1]); v1[2] = gelu_tanh(v1[2]); v1[3] = gelu_tanh(v1[3]);
;                             *(u32x4*)(dst + bj * HALF) = PK8(v0, v1); }
.LBB0_365:
	s_andn2_b64 vcc, exec, s[4:5]
	s_cbranch_vccnz .LBB0_367
	v_lshlrev_b64 v[112:113], 11, v[158:159]
	v_lshl_add_u64 v[112:113], s[22:23], 0, v[112:113]
	v_lshl_add_u64 v[116:117], v[156:157], 1, v[112:113]
	v_mul_f32_e32 v112, 0xbdd2d3e7, v132
	v_fmaak_f32 v112, v132, v112, 0xc0135761
	v_mul_f32_e32 v112, v132, v112
	v_exp_f32_e32 v120, v112
	v_mul_f32_e32 v112, 0xbdd2d3e7, v133
	v_fmaak_f32 v112, v133, v112, 0xc0135761
	v_mul_f32_e32 v112, v133, v112
	v_mov_b32_e32 v167, v166
	v_exp_f32_e32 v121, v112
	v_pk_mul_f32 v[112:113], v[122:123], v[166:167]
	v_mul_f32_e32 v122, 0xbdd2d3e7, v134
	v_mul_f32_e32 v123, 0xbdd2d3e7, v135
	v_mul_f32_e32 v126, 0xbdd2d3e7, v136
	v_mul_f32_e32 v127, 0xbdd2d3e7, v137
	v_mul_f32_e32 v130, 0xbdd2d3e7, v112
	v_mul_f32_e32 v131, 0xbdd2d3e7, v113
	v_fmaak_f32 v122, v134, v122, 0xc0135761
	v_fmaak_f32 v123, v135, v123, 0xc0135761
	v_fmaak_f32 v126, v136, v126, 0xc0135761
	v_fmaak_f32 v127, v137, v127, 0xc0135761
	v_fmaak_f32 v130, v112, v130, 0xc0135761
	v_fmaak_f32 v131, v113, v131, 0xc0135761
	v_mul_f32_e32 v122, v134, v122
	v_mul_f32_e32 v123, v135, v123
	v_mul_f32_e32 v126, v136, v126
	v_mul_f32_e32 v127, v137, v127
	v_mul_f32_e32 v130, v112, v130
	v_mul_f32_e32 v131, v113, v131
	v_exp_f32_e32 v122, v122
	v_exp_f32_e32 v123, v123
	v_exp_f32_e32 v126, v126
	v_exp_f32_e32 v127, v127
	v_exp_f32_e32 v130, v130
	v_exp_f32_e32 v131, v131
	v_add_f32_e32 v120, 1.0, v120
	v_add_f32_e32 v121, 1.0, v121
	v_add_f32_e32 v122, 1.0, v122
	v_add_f32_e32 v123, 1.0, v123
	v_add_f32_e32 v126, 1.0, v126
	v_add_f32_e32 v127, 1.0, v127
	v_add_f32_e32 v130, 1.0, v130
	v_add_f32_e32 v131, 1.0, v131
	v_rcp_f32_e32 v120, v120
	v_rcp_f32_e32 v121, v121
	v_rcp_f32_e32 v122, v122
	v_rcp_f32_e32 v123, v123
	v_rcp_f32_e32 v126, v126
	v_rcp_f32_e32 v127, v127
	v_rcp_f32_e32 v130, v130
	v_rcp_f32_e32 v131, v131
	v_pk_mul_f32 v[120:121], v[132:133], v[120:121]
	v_pk_mul_f32 v[122:123], v[134:135], v[122:123]
	v_pk_mul_f32 v[126:127], v[136:137], v[126:127]
	v_pk_mul_f32 v[112:113], v[112:113], v[130:131]
	v_cvt_pk_bf16_f32 v120, v120, v121
	v_cvt_pk_bf16_f32 v121, v122, v123
	v_cvt_pk_bf16_f32 v122, v126, v127
	v_cvt_pk_bf16_f32 v123, v112, v113
	v_pk_mul_f32 v[112:113], v[118:119], v[166:167]
	v_pk_mul_f32 v[114:115], v[114:115], v[166:167]
	global_store_dwordx4 v[116:117], v[120:123], off
	v_mul_f32_e32 v118, 0xbdd2d3e7, v128
	v_mul_f32_e32 v119, 0xbdd2d3e7, v129
	v_mul_f32_e32 v120, 0xbdd2d3e7, v112
	v_mul_f32_e32 v121, 0xbdd2d3e7, v113
	v_mul_f32_e32 v122, 0xbdd2d3e7, v124
	v_mul_f32_e32 v123, 0xbdd2d3e7, v125
	v_mul_f32_e32 v126, 0xbdd2d3e7, v114
	v_mul_f32_e32 v127, 0xbdd2d3e7, v115
	v_fmaak_f32 v118, v128, v118, 0xc0135761
	v_fmaak_f32 v119, v129, v119, 0xc0135761
	v_fmaak_f32 v120, v112, v120, 0xc0135761
	v_fmaak_f32 v121, v113, v121, 0xc0135761
	v_fmaak_f32 v122, v124, v122, 0xc0135761
	v_fmaak_f32 v123, v125, v123, 0xc0135761
	v_fmaak_f32 v126, v114, v126, 0xc0135761
	v_fmaak_f32 v127, v115, v127, 0xc0135761
	v_mul_f32_e32 v118, v128, v118
	v_mul_f32_e32 v119, v129, v119
	v_mul_f32_e32 v120, v112, v120
	v_mul_f32_e32 v121, v113, v121
	v_mul_f32_e32 v122, v124, v122
	v_mul_f32_e32 v123, v125, v123
	v_mul_f32_e32 v126, v114, v126
	v_mul_f32_e32 v127, v115, v127
	v_exp_f32_e32 v118, v118
	v_exp_f32_e32 v119, v119
	v_exp_f32_e32 v120, v120
	v_exp_f32_e32 v121, v121
	v_exp_f32_e32 v122, v122
	v_exp_f32_e32 v123, v123
	v_exp_f32_e32 v126, v126
	v_exp_f32_e32 v127, v127
	v_add_f32_e32 v118, 1.0, v118
	v_add_f32_e32 v119, 1.0, v119
	v_add_f32_e32 v120, 1.0, v120
	v_add_f32_e32 v121, 1.0, v121
	v_add_f32_e32 v122, 1.0, v122
	v_add_f32_e32 v123, 1.0, v123
	v_add_f32_e32 v126, 1.0, v126
	v_add_f32_e32 v127, 1.0, v127
	v_rcp_f32_e32 v118, v118
	v_rcp_f32_e32 v119, v119
	v_rcp_f32_e32 v120, v120
	v_rcp_f32_e32 v121, v121
	v_rcp_f32_e32 v122, v122
	v_rcp_f32_e32 v123, v123
	v_rcp_f32_e32 v126, v126
	v_rcp_f32_e32 v127, v127
	v_pk_mul_f32 v[118:119], v[128:129], v[118:119]
	v_pk_mul_f32 v[120:121], v[112:113], v[120:121]
	v_pk_mul_f32 v[122:123], v[124:125], v[122:123]
	v_pk_mul_f32 v[124:125], v[114:115], v[126:127]
	v_cvt_pk_bf16_f32 v112, v118, v119
	v_cvt_pk_bf16_f32 v113, v120, v121
	v_cvt_pk_bf16_f32 v114, v122, v123
	v_cvt_pk_bf16_f32 v115, v124, v125
	global_store_dwordx4 v[116:117], v[112:115], off offset:256

; DI float gelu_tanh(float x) { const float t = x * (1.5957691216f + 0.0713548163f * x * x); return x * __builtin_amdgcn_rcpf(1.f + __builtin_amdgcn_exp2f(-1.4426950409f * t)); }
; #define ROWS8 _Pragma("unroll") for (int ai = 0; ai < 2; ++ai) _Pragma("unroll") for (int m = 0; m < 4; ++m) if (ai == 0 || !hf)
; #define PK8(v0, v1) ({ const u32x2 h0_ = pk4(v0), h1_ = pk4(v1); (u32x4){h0_.x, h0_.y, h1_.x, h1_.y}; })
;     DI void operator()(const Acc& acc, const Unit& u, int wr, int wc, int fr, int fq) const {
;     ...
;                 ROWS8 { const int r = row0 + ai * HALF + m * 16; const float rs = rsv[ai][m];
;                     if (u.pn < 4) { bf16_t* dst = WSB(OFF_U) + (size_t)r * 1024 + colp;
; #pragma unroll
;                         for (int bj = 0; bj < 2; ++bj) { f32x4 v0 = acc[ai][bj][m][0] * rs, v1 = acc[ai][bj][m][1] * rs;
;                             v0[0] = gelu_tanh(v0[0]); v0[1] = gelu_tanh(v0[1]); v0[2] = gelu_tanh(v0[2]); v0[3] = gelu_tanh(v0[3]);
;                             v1[0] = gelu_tanh(v1[0]); v1[1] = gelu_tanh(v1[1]); v1[2] = gelu_tanh(v1[2]); v1[3] = gelu_tanh(v1[3]);
;                             *(u32x4*)(dst + bj * HALF) = PK8(v0, v1); }
.LBB0_369:
	s_andn2_b64 vcc, exec, s[48:49]
	s_cbranch_vccnz .LBB0_371
	v_lshlrev_b64 v[96:97], 11, v[164:165]
	v_lshl_add_u64 v[96:97], s[22:23], 0, v[96:97]
	v_lshl_add_u64 v[100:101], v[156:157], 1, v[96:97]
	v_mul_f32_e32 v96, 0xbdd2d3e7, v116
	v_fmaak_f32 v96, v116, v96, 0xc0135761
	v_mul_f32_e32 v96, v116, v96
	v_exp_f32_e32 v104, v96
	v_mul_f32_e32 v96, 0xbdd2d3e7, v117
	v_fmaak_f32 v96, v117, v96, 0xc0135761
	v_mul_f32_e32 v96, v117, v96
	v_mov_b32_e32 v125, v124
	v_exp_f32_e32 v105, v96
	v_pk_mul_f32 v[96:97], v[106:107], v[124:125]
	v_mul_f32_e32 v106, 0xbdd2d3e7, v118
	v_mul_f32_e32 v107, 0xbdd2d3e7, v119
	v_mul_f32_e32 v110, 0xbdd2d3e7, v120
	v_mul_f32_e32 v111, 0xbdd2d3e7, v121
	v_mul_f32_e32 v114, 0xbdd2d3e7, v96
	v_mul_f32_e32 v115, 0xbdd2d3e7, v97
	v_fmaak_f32 v106, v118, v106, 0xc0135761
	v_fmaak_f32 v107, v119, v107, 0xc0135761
	v_fmaak_f32 v110, v120, v110, 0xc0135761
	v_fmaak_f32 v111, v121, v111, 0xc0135761
	v_fmaak_f32 v114, v96, v114, 0xc0135761
	v_fmaak_f32 v115, v97, v115, 0xc0135761
	v_mul_f32_e32 v106, v118, v106
	v_mul_f32_e32 v107, v119, v107
	v_mul_f32_e32 v110, v120, v110
	v_mul_f32_e32 v111, v121, v111
	v_mul_f32_e32 v114, v96, v114
	v_mul_f32_e32 v115, v97, v115
	v_exp_f32_e32 v106, v106
	v_exp_f32_e32 v107, v107
	v_exp_f32_e32 v110, v110
	v_exp_f32_e32 v111, v111
	v_exp_f32_e32 v114, v114
	v_exp_f32_e32 v115, v115
	v_add_f32_e32 v104, 1.0, v104
	v_add_f32_e32 v105, 1.0, v105
	v_add_f32_e32 v106, 1.0, v106
	v_add_f32_e32 v107, 1.0, v107
	v_add_f32_e32 v110, 1.0, v110
	v_add_f32_e32 v111, 1.0, v111
	v_add_f32_e32 v114, 1.0, v114
	v_add_f32_e32 v115, 1.0, v115
	v_rcp_f32_e32 v104, v104
	v_rcp_f32_e32 v105, v105
	v_rcp_f32_e32 v106, v106
	v_rcp_f32_e32 v107, v107
	v_rcp_f32_e32 v110, v110
	v_rcp_f32_e32 v111, v111
	v_rcp_f32_e32 v114, v114
	v_rcp_f32_e32 v115, v115
	v_pk_mul_f32 v[104:105], v[116:117], v[104:105]
	v_pk_mul_f32 v[106:107], v[118:119], v[106:107]
	v_pk_mul_f32 v[110:111], v[120:121], v[110:111]
	v_pk_mul_f32 v[96:97], v[96:97], v[114:115]
	v_cvt_pk_bf16_f32 v104, v104, v105
	v_cvt_pk_bf16_f32 v105, v106, v107
	v_cvt_pk_bf16_f32 v106, v110, v111
	v_cvt_pk_bf16_f32 v107, v96, v97
	v_pk_mul_f32 v[96:97], v[102:103], v[124:125]
	v_pk_mul_f32 v[98:99], v[98:99], v[124:125]
	global_store_dwordx4 v[100:101], v[104:107], off
	v_mul_f32_e32 v102, 0xbdd2d3e7, v112
	v_mul_f32_e32 v103, 0xbdd2d3e7, v113
	v_mul_f32_e32 v104, 0xbdd2d3e7, v96
	v_mul_f32_e32 v105, 0xbdd2d3e7, v97
	v_mul_f32_e32 v106, 0xbdd2d3e7, v108
	v_mul_f32_e32 v107, 0xbdd2d3e7, v109
	v_mul_f32_e32 v110, 0xbdd2d3e7, v98
	v_mul_f32_e32 v111, 0xbdd2d3e7, v99
	v_fmaak_f32 v102, v112, v102, 0xc0135761
	v_fmaak_f32 v103, v113, v103, 0xc0135761
	v_fmaak_f32 v104, v96, v104, 0xc0135761
	v_fmaak_f32 v105, v97, v105, 0xc0135761
	v_fmaak_f32 v106, v108, v106, 0xc0135761
	v_fmaak_f32 v107, v109, v107, 0xc0135761
	v_fmaak_f32 v110, v98, v110, 0xc0135761
	v_fmaak_f32 v111, v99, v111, 0xc0135761
	v_mul_f32_e32 v102, v112, v102
	v_mul_f32_e32 v103, v113, v103
	v_mul_f32_e32 v104, v96, v104
	v_mul_f32_e32 v105, v97, v105
	v_mul_f32_e32 v106, v108, v106
	v_mul_f32_e32 v107, v109, v107
	v_mul_f32_e32 v110, v98, v110
	v_mul_f32_e32 v111, v99, v111
	v_exp_f32_e32 v102, v102
	v_exp_f32_e32 v103, v103
	v_exp_f32_e32 v104, v104
	v_exp_f32_e32 v105, v105
	v_exp_f32_e32 v106, v106
	v_exp_f32_e32 v107, v107
	v_exp_f32_e32 v110, v110
	v_exp_f32_e32 v111, v111
	v_add_f32_e32 v102, 1.0, v102
	v_add_f32_e32 v103, 1.0, v103
	v_add_f32_e32 v104, 1.0, v104
	v_add_f32_e32 v105, 1.0, v105
	v_add_f32_e32 v106, 1.0, v106
	v_add_f32_e32 v107, 1.0, v107
	v_add_f32_e32 v110, 1.0, v110
	v_add_f32_e32 v111, 1.0, v111
	v_rcp_f32_e32 v102, v102
	v_rcp_f32_e32 v103, v103
	v_rcp_f32_e32 v104, v104
	v_rcp_f32_e32 v105, v105
	v_rcp_f32_e32 v106, v106
	v_rcp_f32_e32 v107, v107
	v_rcp_f32_e32 v110, v110
	v_rcp_f32_e32 v111, v111
	v_pk_mul_f32 v[102:103], v[112:113], v[102:103]
	v_pk_mul_f32 v[104:105], v[96:97], v[104:105]
	v_pk_mul_f32 v[106:107], v[108:109], v[106:107]
	v_pk_mul_f32 v[108:109], v[98:99], v[110:111]
	v_cvt_pk_bf16_f32 v96, v102, v103
	v_cvt_pk_bf16_f32 v97, v104, v105
	v_cvt_pk_bf16_f32 v98, v106, v107
	v_cvt_pk_bf16_f32 v99, v108, v109
	global_store_dwordx4 v[100:101], v[96:99], off offset:256

; DI float gelu_tanh(float x) { const float t = x * (1.5957691216f + 0.0713548163f * x * x); return x * __builtin_amdgcn_rcpf(1.f + __builtin_amdgcn_exp2f(-1.4426950409f * t)); }
; #define ROWS8 _Pragma("unroll") for (int ai = 0; ai < 2; ++ai) _Pragma("unroll") for (int m = 0; m < 4; ++m) if (ai == 0 || !hf)
; #define PK8(v0, v1) ({ const u32x2 h0_ = pk4(v0), h1_ = pk4(v1); (u32x4){h0_.x, h0_.y, h1_.x, h1_.y}; })
;     DI void operator()(const Acc& acc, const Unit& u, int wr, int wc, int fr, int fq) const {
;     ...
;                 ROWS8 { const int r = row0 + ai * HALF + m * 16; const float rs = rsv[ai][m];
;                     if (u.pn < 4) { bf16_t* dst = WSB(OFF_U) + (size_t)r * 1024 + colp;
; #pragma unroll
;                         for (int bj = 0; bj < 2; ++bj) { f32x4 v0 = acc[ai][bj][m][0] * rs, v1 = acc[ai][bj][m][1] * rs;
;                             v0[0] = gelu_tanh(v0[0]); v0[1] = gelu_tanh(v0[1]); v0[2] = gelu_tanh(v0[2]); v0[3] = gelu_tanh(v0[3]);
;                             v1[0] = gelu_tanh(v1[0]); v1[1] = gelu_tanh(v1[1]); v1[2] = gelu_tanh(v1[2]); v1[3] = gelu_tanh(v1[3]);
;                             *(u32x4*)(dst + bj * HALF) = PK8(v0, v1); }
.LBB0_373:
	s_andn2_b64 vcc, exec, s[46:47]
	s_cbranch_vccnz .LBB0_375
	v_lshlrev_b64 v[80:81], 11, v[162:163]
	v_lshl_add_u64 v[80:81], s[22:23], 0, v[80:81]
	v_lshl_add_u64 v[84:85], v[156:157], 1, v[80:81]
	v_mul_f32_e32 v80, 0xbdd2d3e7, v100
	v_fmaak_f32 v80, v100, v80, 0xc0135761
	v_mul_f32_e32 v80, v100, v80
	v_exp_f32_e32 v88, v80
	v_mul_f32_e32 v80, 0xbdd2d3e7, v101
	v_fmaak_f32 v80, v101, v80, 0xc0135761
	v_mul_f32_e32 v80, v101, v80
	v_mov_b32_e32 v109, v108
	v_exp_f32_e32 v89, v80
	v_pk_mul_f32 v[80:81], v[90:91], v[108:109]
	v_mul_f32_e32 v90, 0xbdd2d3e7, v102
	v_mul_f32_e32 v91, 0xbdd2d3e7, v103
	v_mul_f32_e32 v94, 0xbdd2d3e7, v104
	v_mul_f32_e32 v95, 0xbdd2d3e7, v105
	v_mul_f32_e32 v98, 0xbdd2d3e7, v80
	v_mul_f32_e32 v99, 0xbdd2d3e7, v81
	v_fmaak_f32 v90, v102, v90, 0xc0135761
	v_fmaak_f32 v91, v103, v91, 0xc0135761
	v_fmaak_f32 v94, v104, v94, 0xc0135761
	v_fmaak_f32 v95, v105, v95, 0xc0135761
	v_fmaak_f32 v98, v80, v98, 0xc0135761
	v_fmaak_f32 v99, v81, v99, 0xc0135761
	v_mul_f32_e32 v90, v102, v90
	v_mul_f32_e32 v91, v103, v91
	v_mul_f32_e32 v94, v104, v94
	v_mul_f32_e32 v95, v105, v95
	v_mul_f32_e32 v98, v80, v98
	v_mul_f32_e32 v99, v81, v99
	v_exp_f32_e32 v90, v90
	v_exp_f32_e32 v91, v91
	v_exp_f32_e32 v94, v94
	v_exp_f32_e32 v95, v95
	v_exp_f32_e32 v98, v98
	v_exp_f32_e32 v99, v99
	v_add_f32_e32 v88, 1.0, v88
	v_add_f32_e32 v89, 1.0, v89
	v_add_f32_e32 v90, 1.0, v90
	v_add_f32_e32 v91, 1.0, v91
	v_add_f32_e32 v94, 1.0, v94
	v_add_f32_e32 v95, 1.0, v95
	v_add_f32_e32 v98, 1.0, v98
	v_add_f32_e32 v99, 1.0, v99
	v_rcp_f32_e32 v88, v88
	v_rcp_f32_e32 v89, v89
	v_rcp_f32_e32 v90, v90
	v_rcp_f32_e32 v91, v91
	v_rcp_f32_e32 v94, v94
	v_rcp_f32_e32 v95, v95
	v_rcp_f32_e32 v98, v98
	v_rcp_f32_e32 v99, v99
	v_pk_mul_f32 v[88:89], v[100:101], v[88:89]
	v_pk_mul_f32 v[90:91], v[102:103], v[90:91]
	v_pk_mul_f32 v[94:95], v[104:105], v[94:95]
	v_pk_mul_f32 v[80:81], v[80:81], v[98:99]
	v_cvt_pk_bf16_f32 v88, v88, v89
	v_cvt_pk_bf16_f32 v89, v90, v91
	v_cvt_pk_bf16_f32 v90, v94, v95
	v_cvt_pk_bf16_f32 v91, v80, v81
	v_pk_mul_f32 v[80:81], v[86:87], v[108:109]
	v_pk_mul_f32 v[82:83], v[82:83], v[108:109]
	global_store_dwordx4 v[84:85], v[88:91], off
	v_mul_f32_e32 v86, 0xbdd2d3e7, v96
	v_mul_f32_e32 v87, 0xbdd2d3e7, v97
	v_mul_f32_e32 v88, 0xbdd2d3e7, v80
	v_mul_f32_e32 v89, 0xbdd2d3e7, v81
	v_mul_f32_e32 v90, 0xbdd2d3e7, v92
	v_mul_f32_e32 v91, 0xbdd2d3e7, v93
	v_mul_f32_e32 v94, 0xbdd2d3e7, v82
	v_mul_f32_e32 v95, 0xbdd2d3e7, v83
	v_fmaak_f32 v86, v96, v86, 0xc0135761
	v_fmaak_f32 v87, v97, v87, 0xc0135761
	v_fmaak_f32 v88, v80, v88, 0xc0135761
	v_fmaak_f32 v89, v81, v89, 0xc0135761
	v_fmaak_f32 v90, v92, v90, 0xc0135761
	v_fmaak_f32 v91, v93, v91, 0xc0135761
	v_fmaak_f32 v94, v82, v94, 0xc0135761
	v_fmaak_f32 v95, v83, v95, 0xc0135761
	v_mul_f32_e32 v86, v96, v86
	v_mul_f32_e32 v87, v97, v87
	v_mul_f32_e32 v88, v80, v88
	v_mul_f32_e32 v89, v81, v89
	v_mul_f32_e32 v90, v92, v90
	v_mul_f32_e32 v91, v93, v91
	v_mul_f32_e32 v94, v82, v94
	v_mul_f32_e32 v95, v83, v95
	v_exp_f32_e32 v86, v86
	v_exp_f32_e32 v87, v87
	v_exp_f32_e32 v88, v88
	v_exp_f32_e32 v89, v89
	v_exp_f32_e32 v90, v90
	v_exp_f32_e32 v91, v91
	v_exp_f32_e32 v94, v94
	v_exp_f32_e32 v95, v95
	v_add_f32_e32 v86, 1.0, v86
	v_add_f32_e32 v87, 1.0, v87
	v_add_f32_e32 v88, 1.0, v88
	v_add_f32_e32 v89, 1.0, v89
	v_add_f32_e32 v90, 1.0, v90
	v_add_f32_e32 v91, 1.0, v91
	v_add_f32_e32 v94, 1.0, v94
	v_add_f32_e32 v95, 1.0, v95
	v_rcp_f32_e32 v86, v86
	v_rcp_f32_e32 v87, v87
	v_rcp_f32_e32 v88, v88
	v_rcp_f32_e32 v89, v89
	v_rcp_f32_e32 v90, v90
	v_rcp_f32_e32 v91, v91
	v_rcp_f32_e32 v94, v94
	v_rcp_f32_e32 v95, v95
	v_pk_mul_f32 v[86:87], v[96:97], v[86:87]
	v_pk_mul_f32 v[88:89], v[80:81], v[88:89]
	v_pk_mul_f32 v[90:91], v[92:93], v[90:91]
	v_pk_mul_f32 v[92:93], v[82:83], v[94:95]
	v_cvt_pk_bf16_f32 v80, v86, v87
	v_cvt_pk_bf16_f32 v81, v88, v89
	v_cvt_pk_bf16_f32 v82, v90, v91
	v_cvt_pk_bf16_f32 v83, v92, v93
	global_store_dwordx4 v[84:85], v[80:83], off offset:256

; DI float gelu_tanh(float x) { const float t = x * (1.5957691216f + 0.0713548163f * x * x); return x * __builtin_amdgcn_rcpf(1.f + __builtin_amdgcn_exp2f(-1.4426950409f * t)); }
; #define ROWS8 _Pragma("unroll") for (int ai = 0; ai < 2; ++ai) _Pragma("unroll") for (int m = 0; m < 4; ++m) if (ai == 0 || !hf)
; #define PK8(v0, v1) ({ const u32x2 h0_ = pk4(v0), h1_ = pk4(v1); (u32x4){h0_.x, h0_.y, h1_.x, h1_.y}; })
;     DI void operator()(const Acc& acc, const Unit& u, int wr, int wc, int fr, int fq) const {
;     ...
;                 ROWS8 { const int r = row0 + ai * HALF + m * 16; const float rs = rsv[ai][m];
;                     if (u.pn < 4) { bf16_t* dst = WSB(OFF_U) + (size_t)r * 1024 + colp;
; #pragma unroll
;                         for (int bj = 0; bj < 2; ++bj) { f32x4 v0 = acc[ai][bj][m][0] * rs, v1 = acc[ai][bj][m][1] * rs;
;                             v0[0] = gelu_tanh(v0[0]); v0[1] = gelu_tanh(v0[1]); v0[2] = gelu_tanh(v0[2]); v0[3] = gelu_tanh(v0[3]);
;                             v1[0] = gelu_tanh(v1[0]); v1[1] = gelu_tanh(v1[1]); v1[2] = gelu_tanh(v1[2]); v1[3] = gelu_tanh(v1[3]);
;                             *(u32x4*)(dst + bj * HALF) = PK8(v0, v1); }
.LBB0_377:
	s_andn2_b64 vcc, exec, s[46:47]
	s_cbranch_vccnz .LBB0_379
	v_lshlrev_b64 v[64:65], 11, v[160:161]
	v_lshl_add_u64 v[64:65], s[22:23], 0, v[64:65]
	v_lshl_add_u64 v[68:69], v[156:157], 1, v[64:65]
	v_mul_f32_e32 v64, 0xbdd2d3e7, v84
	v_fmaak_f32 v64, v84, v64, 0xc0135761
	v_mul_f32_e32 v64, v84, v64
	v_exp_f32_e32 v72, v64
	v_mul_f32_e32 v64, 0xbdd2d3e7, v85
	v_fmaak_f32 v64, v85, v64, 0xc0135761
	v_mul_f32_e32 v64, v85, v64
	v_mov_b32_e32 v93, v92
	v_exp_f32_e32 v73, v64
	v_pk_mul_f32 v[64:65], v[74:75], v[92:93]
	v_mul_f32_e32 v74, 0xbdd2d3e7, v86
	v_mul_f32_e32 v75, 0xbdd2d3e7, v87
	v_mul_f32_e32 v78, 0xbdd2d3e7, v88
	v_mul_f32_e32 v79, 0xbdd2d3e7, v89
	v_mul_f32_e32 v82, 0xbdd2d3e7, v64
	v_mul_f32_e32 v83, 0xbdd2d3e7, v65
	v_fmaak_f32 v74, v86, v74, 0xc0135761
	v_fmaak_f32 v75, v87, v75, 0xc0135761
	v_fmaak_f32 v78, v88, v78, 0xc0135761
	v_fmaak_f32 v79, v89, v79, 0xc0135761
	v_fmaak_f32 v82, v64, v82, 0xc0135761
	v_fmaak_f32 v83, v65, v83, 0xc0135761
	v_mul_f32_e32 v74, v86, v74
	v_mul_f32_e32 v75, v87, v75
	v_mul_f32_e32 v78, v88, v78
	v_mul_f32_e32 v79, v89, v79
	v_mul_f32_e32 v82, v64, v82
	v_mul_f32_e32 v83, v65, v83
	v_exp_f32_e32 v74, v74
	v_exp_f32_e32 v75, v75
	v_exp_f32_e32 v78, v78
	v_exp_f32_e32 v79, v79
	v_exp_f32_e32 v82, v82
	v_exp_f32_e32 v83, v83
	v_add_f32_e32 v72, 1.0, v72
	v_add_f32_e32 v73, 1.0, v73
	v_add_f32_e32 v74, 1.0, v74
	v_add_f32_e32 v75, 1.0, v75
	v_add_f32_e32 v78, 1.0, v78
	v_add_f32_e32 v79, 1.0, v79
	v_add_f32_e32 v82, 1.0, v82
	v_add_f32_e32 v83, 1.0, v83
	v_rcp_f32_e32 v72, v72
	v_rcp_f32_e32 v73, v73
	v_rcp_f32_e32 v74, v74
	v_rcp_f32_e32 v75, v75
	v_rcp_f32_e32 v78, v78
	v_rcp_f32_e32 v79, v79
	v_rcp_f32_e32 v82, v82
	v_rcp_f32_e32 v83, v83
	v_pk_mul_f32 v[72:73], v[84:85], v[72:73]
	v_pk_mul_f32 v[74:75], v[86:87], v[74:75]
	v_pk_mul_f32 v[78:79], v[88:89], v[78:79]
	v_pk_mul_f32 v[64:65], v[64:65], v[82:83]
	v_cvt_pk_bf16_f32 v72, v72, v73
	v_cvt_pk_bf16_f32 v73, v74, v75
	v_cvt_pk_bf16_f32 v74, v78, v79
	v_cvt_pk_bf16_f32 v75, v64, v65
	v_pk_mul_f32 v[64:65], v[70:71], v[92:93]
	v_pk_mul_f32 v[66:67], v[66:67], v[92:93]
	global_store_dwordx4 v[68:69], v[72:75], off
	v_mul_f32_e32 v70, 0xbdd2d3e7, v80
	v_mul_f32_e32 v71, 0xbdd2d3e7, v81
	v_mul_f32_e32 v72, 0xbdd2d3e7, v64
	v_mul_f32_e32 v73, 0xbdd2d3e7, v65
	v_mul_f32_e32 v74, 0xbdd2d3e7, v76
	v_mul_f32_e32 v75, 0xbdd2d3e7, v77
	v_mul_f32_e32 v78, 0xbdd2d3e7, v66
	v_mul_f32_e32 v79, 0xbdd2d3e7, v67
	v_fmaak_f32 v70, v80, v70, 0xc0135761
	v_fmaak_f32 v71, v81, v71, 0xc0135761
	v_fmaak_f32 v72, v64, v72, 0xc0135761
	v_fmaak_f32 v73, v65, v73, 0xc0135761
	v_fmaak_f32 v74, v76, v74, 0xc0135761
	v_fmaak_f32 v75, v77, v75, 0xc0135761
	v_fmaak_f32 v78, v66, v78, 0xc0135761
	v_fmaak_f32 v79, v67, v79, 0xc0135761
	v_mul_f32_e32 v70, v80, v70
	v_mul_f32_e32 v71, v81, v71
	v_mul_f32_e32 v72, v64, v72
	v_mul_f32_e32 v73, v65, v73
	v_mul_f32_e32 v74, v76, v74
	v_mul_f32_e32 v75, v77, v75
	v_mul_f32_e32 v78, v66, v78
	v_mul_f32_e32 v79, v67, v79
	v_exp_f32_e32 v70, v70
	v_exp_f32_e32 v71, v71
	v_exp_f32_e32 v72, v72
	v_exp_f32_e32 v73, v73
	v_exp_f32_e32 v74, v74
	v_exp_f32_e32 v75, v75
	v_exp_f32_e32 v78, v78
	v_exp_f32_e32 v79, v79
	v_add_f32_e32 v70, 1.0, v70
	v_add_f32_e32 v71, 1.0, v71
	v_add_f32_e32 v72, 1.0, v72
	v_add_f32_e32 v73, 1.0, v73
	v_add_f32_e32 v74, 1.0, v74
	v_add_f32_e32 v75, 1.0, v75
	v_add_f32_e32 v78, 1.0, v78
	v_add_f32_e32 v79, 1.0, v79
	v_rcp_f32_e32 v70, v70
	v_rcp_f32_e32 v71, v71
	v_rcp_f32_e32 v72, v72
	v_rcp_f32_e32 v73, v73
	v_rcp_f32_e32 v74, v74
	v_rcp_f32_e32 v75, v75
	v_rcp_f32_e32 v78, v78
	v_rcp_f32_e32 v79, v79
	v_pk_mul_f32 v[70:71], v[80:81], v[70:71]
	v_pk_mul_f32 v[72:73], v[64:65], v[72:73]
	v_pk_mul_f32 v[74:75], v[76:77], v[74:75]
	v_pk_mul_f32 v[76:77], v[66:67], v[78:79]
	v_cvt_pk_bf16_f32 v64, v70, v71
	v_cvt_pk_bf16_f32 v65, v72, v73
	v_cvt_pk_bf16_f32 v66, v74, v75
	v_cvt_pk_bf16_f32 v67, v76, v77
	global_store_dwordx4 v[68:69], v[64:67], off offset:256

; DI float gelu_tanh(float x) { const float t = x * (1.5957691216f + 0.0713548163f * x * x); return x * __builtin_amdgcn_rcpf(1.f + __builtin_amdgcn_exp2f(-1.4426950409f * t)); }
; #define ROWS8 _Pragma("unroll") for (int ai = 0; ai < 2; ++ai) _Pragma("unroll") for (int m = 0; m < 4; ++m) if (ai == 0 || !hf)
; #define PK8(v0, v1) ({ const u32x2 h0_ = pk4(v0), h1_ = pk4(v1); (u32x4){h0_.x, h0_.y, h1_.x, h1_.y}; })
;     DI void operator()(const Acc& acc, const Unit& u, int wr, int wc, int fr, int fq) const {
;     ...
;                 ROWS8 { const int r = row0 + ai * HALF + m * 16; const float rs = rsv[ai][m];
;                     if (u.pn < 4) { bf16_t* dst = WSB(OFF_U) + (size_t)r * 1024 + colp;
; #pragma unroll
;                         for (int bj = 0; bj < 2; ++bj) { f32x4 v0 = acc[ai][bj][m][0] * rs, v1 = acc[ai][bj][m][1] * rs;
;                             v0[0] = gelu_tanh(v0[0]); v0[1] = gelu_tanh(v0[1]); v0[2] = gelu_tanh(v0[2]); v0[3] = gelu_tanh(v0[3]);
;                             v1[0] = gelu_tanh(v1[0]); v1[1] = gelu_tanh(v1[1]); v1[2] = gelu_tanh(v1[2]); v1[3] = gelu_tanh(v1[3]);
;                             *(u32x4*)(dst + bj * HALF) = PK8(v0, v1); }
.LBB0_381:
	s_andn2_b64 vcc, exec, s[46:47]
	s_cbranch_vccnz .LBB0_383
	v_lshlrev_b64 v[48:49], 11, v[78:79]
	v_lshl_add_u64 v[48:49], s[22:23], 0, v[48:49]
	v_lshl_add_u64 v[52:53], v[156:157], 1, v[48:49]
	v_mul_f32_e32 v48, 0xbdd2d3e7, v68
	v_fmaak_f32 v48, v68, v48, 0xc0135761
	v_mul_f32_e32 v48, v68, v48
	v_exp_f32_e32 v56, v48
	v_mul_f32_e32 v48, 0xbdd2d3e7, v69
	v_fmaak_f32 v48, v69, v48, 0xc0135761
	v_mul_f32_e32 v48, v69, v48
	v_mov_b32_e32 v77, v76
	v_exp_f32_e32 v57, v48
	v_pk_mul_f32 v[48:49], v[58:59], v[76:77]
	v_mul_f32_e32 v58, 0xbdd2d3e7, v70
	v_mul_f32_e32 v59, 0xbdd2d3e7, v71
	v_mul_f32_e32 v62, 0xbdd2d3e7, v72
	v_mul_f32_e32 v63, 0xbdd2d3e7, v73
	v_mul_f32_e32 v66, 0xbdd2d3e7, v48
	v_mul_f32_e32 v67, 0xbdd2d3e7, v49
	v_fmaak_f32 v58, v70, v58, 0xc0135761
	v_fmaak_f32 v59, v71, v59, 0xc0135761
	v_fmaak_f32 v62, v72, v62, 0xc0135761
	v_fmaak_f32 v63, v73, v63, 0xc0135761
	v_fmaak_f32 v66, v48, v66, 0xc0135761
	v_fmaak_f32 v67, v49, v67, 0xc0135761
	v_mul_f32_e32 v58, v70, v58
	v_mul_f32_e32 v59, v71, v59
	v_mul_f32_e32 v62, v72, v62
	v_mul_f32_e32 v63, v73, v63
	v_mul_f32_e32 v66, v48, v66
	v_mul_f32_e32 v67, v49, v67
	v_exp_f32_e32 v58, v58
	v_exp_f32_e32 v59, v59
	v_exp_f32_e32 v62, v62
	v_exp_f32_e32 v63, v63
	v_exp_f32_e32 v66, v66
	v_exp_f32_e32 v67, v67
	v_add_f32_e32 v56, 1.0, v56
	v_add_f32_e32 v57, 1.0, v57
	v_add_f32_e32 v58, 1.0, v58
	v_add_f32_e32 v59, 1.0, v59
	v_add_f32_e32 v62, 1.0, v62
	v_add_f32_e32 v63, 1.0, v63
	v_add_f32_e32 v66, 1.0, v66
	v_add_f32_e32 v67, 1.0, v67
	v_rcp_f32_e32 v56, v56
	v_rcp_f32_e32 v57, v57
	v_rcp_f32_e32 v58, v58
	v_rcp_f32_e32 v59, v59
	v_rcp_f32_e32 v62, v62
	v_rcp_f32_e32 v63, v63
	v_rcp_f32_e32 v66, v66
	v_rcp_f32_e32 v67, v67
	v_pk_mul_f32 v[56:57], v[68:69], v[56:57]
	v_pk_mul_f32 v[58:59], v[70:71], v[58:59]
	v_pk_mul_f32 v[62:63], v[72:73], v[62:63]
	v_pk_mul_f32 v[48:49], v[48:49], v[66:67]
	v_cvt_pk_bf16_f32 v56, v56, v57
	v_cvt_pk_bf16_f32 v57, v58, v59
	v_cvt_pk_bf16_f32 v58, v62, v63
	v_cvt_pk_bf16_f32 v59, v48, v49
	v_pk_mul_f32 v[48:49], v[54:55], v[76:77]
	v_pk_mul_f32 v[50:51], v[50:51], v[76:77]
	global_store_dwordx4 v[52:53], v[56:59], off
	v_mul_f32_e32 v54, 0xbdd2d3e7, v64
	v_mul_f32_e32 v55, 0xbdd2d3e7, v65
	v_mul_f32_e32 v56, 0xbdd2d3e7, v48
	v_mul_f32_e32 v57, 0xbdd2d3e7, v49
	v_mul_f32_e32 v58, 0xbdd2d3e7, v60
	v_mul_f32_e32 v59, 0xbdd2d3e7, v61
	v_mul_f32_e32 v62, 0xbdd2d3e7, v50
	v_mul_f32_e32 v63, 0xbdd2d3e7, v51
	v_fmaak_f32 v54, v64, v54, 0xc0135761
	v_fmaak_f32 v55, v65, v55, 0xc0135761
	v_fmaak_f32 v56, v48, v56, 0xc0135761
	v_fmaak_f32 v57, v49, v57, 0xc0135761
	v_fmaak_f32 v58, v60, v58, 0xc0135761
	v_fmaak_f32 v59, v61, v59, 0xc0135761
	v_fmaak_f32 v62, v50, v62, 0xc0135761
	v_fmaak_f32 v63, v51, v63, 0xc0135761
	v_mul_f32_e32 v54, v64, v54
	v_mul_f32_e32 v55, v65, v55
	v_mul_f32_e32 v56, v48, v56
	v_mul_f32_e32 v57, v49, v57
	v_mul_f32_e32 v58, v60, v58
	v_mul_f32_e32 v59, v61, v59
	v_mul_f32_e32 v62, v50, v62
	v_mul_f32_e32 v63, v51, v63
	v_exp_f32_e32 v54, v54
	v_exp_f32_e32 v55, v55
	v_exp_f32_e32 v56, v56
	v_exp_f32_e32 v57, v57
	v_exp_f32_e32 v58, v58
	v_exp_f32_e32 v59, v59
	v_exp_f32_e32 v62, v62
	v_exp_f32_e32 v63, v63
	v_add_f32_e32 v54, 1.0, v54
	v_add_f32_e32 v55, 1.0, v55
	v_add_f32_e32 v56, 1.0, v56
	v_add_f32_e32 v57, 1.0, v57
	v_add_f32_e32 v58, 1.0, v58
	v_add_f32_e32 v59, 1.0, v59
	v_add_f32_e32 v62, 1.0, v62
	v_add_f32_e32 v63, 1.0, v63
	v_rcp_f32_e32 v54, v54
	v_rcp_f32_e32 v55, v55
	v_rcp_f32_e32 v56, v56
	v_rcp_f32_e32 v57, v57
	v_rcp_f32_e32 v58, v58
	v_rcp_f32_e32 v59, v59
	v_rcp_f32_e32 v62, v62
	v_rcp_f32_e32 v63, v63
	v_pk_mul_f32 v[54:55], v[64:65], v[54:55]
	v_pk_mul_f32 v[56:57], v[48:49], v[56:57]
	v_pk_mul_f32 v[58:59], v[60:61], v[58:59]
	v_pk_mul_f32 v[60:61], v[50:51], v[62:63]
	v_cvt_pk_bf16_f32 v48, v54, v55
	v_cvt_pk_bf16_f32 v49, v56, v57
	v_cvt_pk_bf16_f32 v50, v58, v59
	v_cvt_pk_bf16_f32 v51, v60, v61
	global_store_dwordx4 v[52:53], v[48:51], off offset:256

; DI float gelu_tanh(float x) { const float t = x * (1.5957691216f + 0.0713548163f * x * x); return x * __builtin_amdgcn_rcpf(1.f + __builtin_amdgcn_exp2f(-1.4426950409f * t)); }
; #define ROWS8 _Pragma("unroll") for (int ai = 0; ai < 2; ++ai) _Pragma("unroll") for (int m = 0; m < 4; ++m) if (ai == 0 || !hf)
; #define PK8(v0, v1) ({ const u32x2 h0_ = pk4(v0), h1_ = pk4(v1); (u32x4){h0_.x, h0_.y, h1_.x, h1_.y}; })
;     DI void operator()(const Acc& acc, const Unit& u, int wr, int wc, int fr, int fq) const {
;     ...
;                 ROWS8 { const int r = row0 + ai * HALF + m * 16; const float rs = rsv[ai][m];
;                     if (u.pn < 4) { bf16_t* dst = WSB(OFF_U) + (size_t)r * 1024 + colp;
; #pragma unroll
;                         for (int bj = 0; bj < 2; ++bj) { f32x4 v0 = acc[ai][bj][m][0] * rs, v1 = acc[ai][bj][m][1] * rs;
;                             v0[0] = gelu_tanh(v0[0]); v0[1] = gelu_tanh(v0[1]); v0[2] = gelu_tanh(v0[2]); v0[3] = gelu_tanh(v0[3]);
;                             v1[0] = gelu_tanh(v1[0]); v1[1] = gelu_tanh(v1[1]); v1[2] = gelu_tanh(v1[2]); v1[3] = gelu_tanh(v1[3]);
;                             *(u32x4*)(dst + bj * HALF) = PK8(v0, v1); }
.LBB0_385:
	s_andn2_b64 vcc, exec, s[46:47]
	s_cbranch_vccnz .LBB0_387
	v_lshlrev_b64 v[32:33], 11, v[62:63]
	v_lshl_add_u64 v[32:33], s[22:23], 0, v[32:33]
	v_lshl_add_u64 v[36:37], v[156:157], 1, v[32:33]
	v_mul_f32_e32 v32, 0xbdd2d3e7, v52
	v_fmaak_f32 v32, v52, v32, 0xc0135761
	v_mul_f32_e32 v32, v52, v32
	v_exp_f32_e32 v40, v32
	v_mul_f32_e32 v32, 0xbdd2d3e7, v53
	v_fmaak_f32 v32, v53, v32, 0xc0135761
	v_mul_f32_e32 v32, v53, v32
	v_mov_b32_e32 v61, v60
	v_exp_f32_e32 v41, v32
	v_pk_mul_f32 v[32:33], v[42:43], v[60:61]
	v_mul_f32_e32 v42, 0xbdd2d3e7, v54
	v_mul_f32_e32 v43, 0xbdd2d3e7, v55
	v_mul_f32_e32 v46, 0xbdd2d3e7, v56
	v_mul_f32_e32 v47, 0xbdd2d3e7, v57
	v_mul_f32_e32 v50, 0xbdd2d3e7, v32
	v_mul_f32_e32 v51, 0xbdd2d3e7, v33
	v_fmaak_f32 v42, v54, v42, 0xc0135761
	v_fmaak_f32 v43, v55, v43, 0xc0135761
	v_fmaak_f32 v46, v56, v46, 0xc0135761
	v_fmaak_f32 v47, v57, v47, 0xc0135761
	v_fmaak_f32 v50, v32, v50, 0xc0135761
	v_fmaak_f32 v51, v33, v51, 0xc0135761
	v_mul_f32_e32 v42, v54, v42
	v_mul_f32_e32 v43, v55, v43
	v_mul_f32_e32 v46, v56, v46
	v_mul_f32_e32 v47, v57, v47
	v_mul_f32_e32 v50, v32, v50
	v_mul_f32_e32 v51, v33, v51
	v_exp_f32_e32 v42, v42
	v_exp_f32_e32 v43, v43
	v_exp_f32_e32 v46, v46
	v_exp_f32_e32 v47, v47
	v_exp_f32_e32 v50, v50
	v_exp_f32_e32 v51, v51
	v_add_f32_e32 v40, 1.0, v40
	v_add_f32_e32 v41, 1.0, v41
	v_add_f32_e32 v42, 1.0, v42
	v_add_f32_e32 v43, 1.0, v43
	v_add_f32_e32 v46, 1.0, v46
	v_add_f32_e32 v47, 1.0, v47
	v_add_f32_e32 v50, 1.0, v50
	v_add_f32_e32 v51, 1.0, v51
	v_rcp_f32_e32 v40, v40
	v_rcp_f32_e32 v41, v41
	v_rcp_f32_e32 v42, v42
	v_rcp_f32_e32 v43, v43
	v_rcp_f32_e32 v46, v46
	v_rcp_f32_e32 v47, v47
	v_rcp_f32_e32 v50, v50
	v_rcp_f32_e32 v51, v51
	v_pk_mul_f32 v[40:41], v[52:53], v[40:41]
	v_pk_mul_f32 v[42:43], v[54:55], v[42:43]
	v_pk_mul_f32 v[46:47], v[56:57], v[46:47]
	v_pk_mul_f32 v[32:33], v[32:33], v[50:51]
	v_cvt_pk_bf16_f32 v40, v40, v41
	v_cvt_pk_bf16_f32 v41, v42, v43
	v_cvt_pk_bf16_f32 v42, v46, v47
	v_cvt_pk_bf16_f32 v43, v32, v33
	v_pk_mul_f32 v[32:33], v[38:39], v[60:61]
	v_pk_mul_f32 v[34:35], v[34:35], v[60:61]
	global_store_dwordx4 v[36:37], v[40:43], off
	v_mul_f32_e32 v38, 0xbdd2d3e7, v48
	v_mul_f32_e32 v39, 0xbdd2d3e7, v49
	v_mul_f32_e32 v40, 0xbdd2d3e7, v32
	v_mul_f32_e32 v41, 0xbdd2d3e7, v33
	v_mul_f32_e32 v42, 0xbdd2d3e7, v44
	v_mul_f32_e32 v43, 0xbdd2d3e7, v45
	v_mul_f32_e32 v46, 0xbdd2d3e7, v34
	v_mul_f32_e32 v47, 0xbdd2d3e7, v35
	v_fmaak_f32 v38, v48, v38, 0xc0135761
	v_fmaak_f32 v39, v49, v39, 0xc0135761
	v_fmaak_f32 v40, v32, v40, 0xc0135761
	v_fmaak_f32 v41, v33, v41, 0xc0135761
	v_fmaak_f32 v42, v44, v42, 0xc0135761
	v_fmaak_f32 v43, v45, v43, 0xc0135761
	v_fmaak_f32 v46, v34, v46, 0xc0135761
	v_fmaak_f32 v47, v35, v47, 0xc0135761
	v_mul_f32_e32 v38, v48, v38
	v_mul_f32_e32 v39, v49, v39
	v_mul_f32_e32 v40, v32, v40
	v_mul_f32_e32 v41, v33, v41
	v_mul_f32_e32 v42, v44, v42
	v_mul_f32_e32 v43, v45, v43
	v_mul_f32_e32 v46, v34, v46
	v_mul_f32_e32 v47, v35, v47
	v_exp_f32_e32 v38, v38
	v_exp_f32_e32 v39, v39
	v_exp_f32_e32 v40, v40
	v_exp_f32_e32 v41, v41
	v_exp_f32_e32 v42, v42
	v_exp_f32_e32 v43, v43
	v_exp_f32_e32 v46, v46
	v_exp_f32_e32 v47, v47
	v_add_f32_e32 v38, 1.0, v38
	v_add_f32_e32 v39, 1.0, v39
	v_add_f32_e32 v40, 1.0, v40
	v_add_f32_e32 v41, 1.0, v41
	v_add_f32_e32 v42, 1.0, v42
	v_add_f32_e32 v43, 1.0, v43
	v_add_f32_e32 v46, 1.0, v46
	v_add_f32_e32 v47, 1.0, v47
	v_rcp_f32_e32 v38, v38
	v_rcp_f32_e32 v39, v39
	v_rcp_f32_e32 v40, v40
	v_rcp_f32_e32 v41, v41
	v_rcp_f32_e32 v42, v42
	v_rcp_f32_e32 v43, v43
	v_rcp_f32_e32 v46, v46
	v_rcp_f32_e32 v47, v47
	v_pk_mul_f32 v[38:39], v[48:49], v[38:39]
	v_pk_mul_f32 v[40:41], v[32:33], v[40:41]
	v_pk_mul_f32 v[42:43], v[44:45], v[42:43]
	v_pk_mul_f32 v[44:45], v[34:35], v[46:47]
	v_cvt_pk_bf16_f32 v32, v38, v39
	v_cvt_pk_bf16_f32 v33, v40, v41
	v_cvt_pk_bf16_f32 v34, v42, v43
	v_cvt_pk_bf16_f32 v35, v44, v45
	global_store_dwordx4 v[36:37], v[32:35], off offset:256

; DI float gelu_tanh(float x) { const float t = x * (1.5957691216f + 0.0713548163f * x * x); return x * __builtin_amdgcn_rcpf(1.f + __builtin_amdgcn_exp2f(-1.4426950409f * t)); }
; #define ROWS8 _Pragma("unroll") for (int ai = 0; ai < 2; ++ai) _Pragma("unroll") for (int m = 0; m < 4; ++m) if (ai == 0 || !hf)
; #define PK8(v0, v1) ({ const u32x2 h0_ = pk4(v0), h1_ = pk4(v1); (u32x4){h0_.x, h0_.y, h1_.x, h1_.y}; })
;     DI void operator()(const Acc& acc, const Unit& u, int wr, int wc, int fr, int fq) const {
;     ...
;                 ROWS8 { const int r = row0 + ai * HALF + m * 16; const float rs = rsv[ai][m];
;                     if (u.pn < 4) { bf16_t* dst = WSB(OFF_U) + (size_t)r * 1024 + colp;
; #pragma unroll
;                         for (int bj = 0; bj < 2; ++bj) { f32x4 v0 = acc[ai][bj][m][0] * rs, v1 = acc[ai][bj][m][1] * rs;
;                             v0[0] = gelu_tanh(v0[0]); v0[1] = gelu_tanh(v0[1]); v0[2] = gelu_tanh(v0[2]); v0[3] = gelu_tanh(v0[3]);
;                             v1[0] = gelu_tanh(v1[0]); v1[1] = gelu_tanh(v1[1]); v1[2] = gelu_tanh(v1[2]); v1[3] = gelu_tanh(v1[3]);
;                             *(u32x4*)(dst + bj * HALF) = PK8(v0, v1); }
.LBB0_389:
	s_andn2_b64 vcc, exec, s[46:47]
	s_cbranch_vccnz .LBB0_391
	v_lshlrev_b64 v[16:17], 11, v[46:47]
	v_lshl_add_u64 v[16:17], s[22:23], 0, v[16:17]
	v_lshl_add_u64 v[20:21], v[156:157], 1, v[16:17]
	v_mul_f32_e32 v16, 0xbdd2d3e7, v36
	v_fmaak_f32 v16, v36, v16, 0xc0135761
	v_mul_f32_e32 v16, v36, v16
	v_exp_f32_e32 v24, v16
	v_mul_f32_e32 v16, 0xbdd2d3e7, v37
	v_fmaak_f32 v16, v37, v16, 0xc0135761
	v_mul_f32_e32 v16, v37, v16
	v_mov_b32_e32 v45, v44
	v_exp_f32_e32 v25, v16
	v_pk_mul_f32 v[16:17], v[26:27], v[44:45]
	v_mul_f32_e32 v26, 0xbdd2d3e7, v38
	v_mul_f32_e32 v27, 0xbdd2d3e7, v39
	v_mul_f32_e32 v30, 0xbdd2d3e7, v40
	v_mul_f32_e32 v31, 0xbdd2d3e7, v41
	v_mul_f32_e32 v34, 0xbdd2d3e7, v16
	v_mul_f32_e32 v35, 0xbdd2d3e7, v17
	v_fmaak_f32 v26, v38, v26, 0xc0135761
	v_fmaak_f32 v27, v39, v27, 0xc0135761
	v_fmaak_f32 v30, v40, v30, 0xc0135761
	v_fmaak_f32 v31, v41, v31, 0xc0135761
	v_fmaak_f32 v34, v16, v34, 0xc0135761
	v_fmaak_f32 v35, v17, v35, 0xc0135761
	v_mul_f32_e32 v26, v38, v26
	v_mul_f32_e32 v27, v39, v27
	v_mul_f32_e32 v30, v40, v30
	v_mul_f32_e32 v31, v41, v31
	v_mul_f32_e32 v34, v16, v34
	v_mul_f32_e32 v35, v17, v35
	v_exp_f32_e32 v26, v26
	v_exp_f32_e32 v27, v27
	v_exp_f32_e32 v30, v30
	v_exp_f32_e32 v31, v31
	v_exp_f32_e32 v34, v34
	v_exp_f32_e32 v35, v35
	v_add_f32_e32 v24, 1.0, v24
	v_add_f32_e32 v25, 1.0, v25
	v_add_f32_e32 v26, 1.0, v26
	v_add_f32_e32 v27, 1.0, v27
	v_add_f32_e32 v30, 1.0, v30
	v_add_f32_e32 v31, 1.0, v31
	v_add_f32_e32 v34, 1.0, v34
	v_add_f32_e32 v35, 1.0, v35
	v_rcp_f32_e32 v24, v24
	v_rcp_f32_e32 v25, v25
	v_rcp_f32_e32 v26, v26
	v_rcp_f32_e32 v27, v27
	v_rcp_f32_e32 v30, v30
	v_rcp_f32_e32 v31, v31
	v_rcp_f32_e32 v34, v34
	v_rcp_f32_e32 v35, v35
	v_pk_mul_f32 v[24:25], v[36:37], v[24:25]
	v_pk_mul_f32 v[26:27], v[38:39], v[26:27]
	v_pk_mul_f32 v[30:31], v[40:41], v[30:31]
	v_pk_mul_f32 v[16:17], v[16:17], v[34:35]
	v_cvt_pk_bf16_f32 v24, v24, v25
	v_cvt_pk_bf16_f32 v25, v26, v27
	v_cvt_pk_bf16_f32 v26, v30, v31
	v_cvt_pk_bf16_f32 v27, v16, v17
	v_pk_mul_f32 v[16:17], v[22:23], v[44:45]
	v_pk_mul_f32 v[18:19], v[18:19], v[44:45]
	global_store_dwordx4 v[20:21], v[24:27], off
	v_mul_f32_e32 v22, 0xbdd2d3e7, v32
	v_mul_f32_e32 v23, 0xbdd2d3e7, v33
	v_mul_f32_e32 v24, 0xbdd2d3e7, v16
	v_mul_f32_e32 v25, 0xbdd2d3e7, v17
	v_mul_f32_e32 v26, 0xbdd2d3e7, v28
	v_mul_f32_e32 v27, 0xbdd2d3e7, v29
	v_mul_f32_e32 v30, 0xbdd2d3e7, v18
	v_mul_f32_e32 v31, 0xbdd2d3e7, v19
	v_fmaak_f32 v22, v32, v22, 0xc0135761
	v_fmaak_f32 v23, v33, v23, 0xc0135761
	v_fmaak_f32 v24, v16, v24, 0xc0135761
	v_fmaak_f32 v25, v17, v25, 0xc0135761
	v_fmaak_f32 v26, v28, v26, 0xc0135761
	v_fmaak_f32 v27, v29, v27, 0xc0135761
	v_fmaak_f32 v30, v18, v30, 0xc0135761
	v_fmaak_f32 v31, v19, v31, 0xc0135761
	v_mul_f32_e32 v22, v32, v22
	v_mul_f32_e32 v23, v33, v23
	v_mul_f32_e32 v24, v16, v24
	v_mul_f32_e32 v25, v17, v25
	v_mul_f32_e32 v26, v28, v26
	v_mul_f32_e32 v27, v29, v27
	v_mul_f32_e32 v30, v18, v30
	v_mul_f32_e32 v31, v19, v31
	v_exp_f32_e32 v22, v22
	v_exp_f32_e32 v23, v23
	v_exp_f32_e32 v24, v24
	v_exp_f32_e32 v25, v25
	v_exp_f32_e32 v26, v26
	v_exp_f32_e32 v27, v27
	v_exp_f32_e32 v30, v30
	v_exp_f32_e32 v31, v31
	v_add_f32_e32 v22, 1.0, v22
	v_add_f32_e32 v23, 1.0, v23
	v_add_f32_e32 v24, 1.0, v24
	v_add_f32_e32 v25, 1.0, v25
	v_add_f32_e32 v26, 1.0, v26
	v_add_f32_e32 v27, 1.0, v27
	v_add_f32_e32 v30, 1.0, v30
	v_add_f32_e32 v31, 1.0, v31
	v_rcp_f32_e32 v22, v22
	v_rcp_f32_e32 v23, v23
	v_rcp_f32_e32 v24, v24
	v_rcp_f32_e32 v25, v25
	v_rcp_f32_e32 v26, v26
	v_rcp_f32_e32 v27, v27
	v_rcp_f32_e32 v30, v30
	v_rcp_f32_e32 v31, v31
	v_pk_mul_f32 v[22:23], v[32:33], v[22:23]
	v_pk_mul_f32 v[24:25], v[16:17], v[24:25]
	v_pk_mul_f32 v[26:27], v[28:29], v[26:27]
	v_pk_mul_f32 v[28:29], v[18:19], v[30:31]
	v_cvt_pk_bf16_f32 v16, v22, v23
	v_cvt_pk_bf16_f32 v17, v24, v25
	v_cvt_pk_bf16_f32 v18, v26, v27
	v_cvt_pk_bf16_f32 v19, v28, v29
	global_store_dwordx4 v[20:21], v[16:19], off offset:256

; DI float gelu_tanh(float x) { const float t = x * (1.5957691216f + 0.0713548163f * x * x); return x * __builtin_amdgcn_rcpf(1.f + __builtin_amdgcn_exp2f(-1.4426950409f * t)); }
; #define ROWS8 _Pragma("unroll") for (int ai = 0; ai < 2; ++ai) _Pragma("unroll") for (int m = 0; m < 4; ++m) if (ai == 0 || !hf)
; #define PK8(v0, v1) ({ const u32x2 h0_ = pk4(v0), h1_ = pk4(v1); (u32x4){h0_.x, h0_.y, h1_.x, h1_.y}; })
;     DI void operator()(const Acc& acc, const Unit& u, int wr, int wc, int fr, int fq) const {
;     ...
;                 ROWS8 { const int r = row0 + ai * HALF + m * 16; const float rs = rsv[ai][m];
;                     if (u.pn < 4) { bf16_t* dst = WSB(OFF_U) + (size_t)r * 1024 + colp;
; #pragma unroll
;                         for (int bj = 0; bj < 2; ++bj) { f32x4 v0 = acc[ai][bj][m][0] * rs, v1 = acc[ai][bj][m][1] * rs;
;                             v0[0] = gelu_tanh(v0[0]); v0[1] = gelu_tanh(v0[1]); v0[2] = gelu_tanh(v0[2]); v0[3] = gelu_tanh(v0[3]);
;                             v1[0] = gelu_tanh(v1[0]); v1[1] = gelu_tanh(v1[1]); v1[2] = gelu_tanh(v1[2]); v1[3] = gelu_tanh(v1[3]);
;                             *(u32x4*)(dst + bj * HALF) = PK8(v0, v1); }
.LBB0_393:
	s_andn2_b64 vcc, exec, s[46:47]
	s_cbranch_vccnz .LBB0_314
	v_lshlrev_b64 v[0:1], 11, v[30:31]
	v_lshl_add_u64 v[0:1], s[22:23], 0, v[0:1]
	v_lshl_add_u64 v[4:5], v[156:157], 1, v[0:1]
	v_mul_f32_e32 v0, 0xbdd2d3e7, v20
	v_fmaak_f32 v0, v20, v0, 0xc0135761
	v_mul_f32_e32 v0, v20, v0
	v_exp_f32_e32 v8, v0
	v_mul_f32_e32 v0, 0xbdd2d3e7, v21
	v_fmaak_f32 v0, v21, v0, 0xc0135761
	v_mul_f32_e32 v0, v21, v0
	v_mov_b32_e32 v29, v28
	v_exp_f32_e32 v9, v0
	v_pk_mul_f32 v[0:1], v[10:11], v[28:29]
	v_mul_f32_e32 v10, 0xbdd2d3e7, v22
	v_mul_f32_e32 v11, 0xbdd2d3e7, v23
	v_mul_f32_e32 v14, 0xbdd2d3e7, v24
	v_mul_f32_e32 v15, 0xbdd2d3e7, v25
	v_mul_f32_e32 v18, 0xbdd2d3e7, v0
	v_mul_f32_e32 v19, 0xbdd2d3e7, v1
	v_fmaak_f32 v10, v22, v10, 0xc0135761
	v_fmaak_f32 v11, v23, v11, 0xc0135761
	v_fmaak_f32 v14, v24, v14, 0xc0135761
	v_fmaak_f32 v15, v25, v15, 0xc0135761
	v_fmaak_f32 v18, v0, v18, 0xc0135761
	v_fmaak_f32 v19, v1, v19, 0xc0135761
	v_mul_f32_e32 v10, v22, v10
	v_mul_f32_e32 v11, v23, v11
	v_mul_f32_e32 v14, v24, v14
	v_mul_f32_e32 v15, v25, v15
	v_mul_f32_e32 v18, v0, v18
	v_mul_f32_e32 v19, v1, v19
	v_exp_f32_e32 v10, v10
	v_exp_f32_e32 v11, v11
	v_exp_f32_e32 v14, v14
	v_exp_f32_e32 v15, v15
	v_exp_f32_e32 v18, v18
	v_exp_f32_e32 v19, v19
	v_add_f32_e32 v8, 1.0, v8
	v_add_f32_e32 v9, 1.0, v9
	v_add_f32_e32 v10, 1.0, v10
	v_add_f32_e32 v11, 1.0, v11
	v_add_f32_e32 v14, 1.0, v14
	v_add_f32_e32 v15, 1.0, v15
	v_add_f32_e32 v18, 1.0, v18
	v_add_f32_e32 v19, 1.0, v19
	v_rcp_f32_e32 v8, v8
	v_rcp_f32_e32 v9, v9
	v_rcp_f32_e32 v10, v10
	v_rcp_f32_e32 v11, v11
	v_rcp_f32_e32 v14, v14
	v_rcp_f32_e32 v15, v15
	v_rcp_f32_e32 v18, v18
	v_rcp_f32_e32 v19, v19
	v_pk_mul_f32 v[8:9], v[20:21], v[8:9]
	v_pk_mul_f32 v[10:11], v[22:23], v[10:11]
	v_pk_mul_f32 v[14:15], v[24:25], v[14:15]
	v_pk_mul_f32 v[0:1], v[0:1], v[18:19]
	v_cvt_pk_bf16_f32 v8, v8, v9
	v_cvt_pk_bf16_f32 v9, v10, v11
	v_cvt_pk_bf16_f32 v10, v14, v15
	v_cvt_pk_bf16_f32 v11, v0, v1
	v_pk_mul_f32 v[0:1], v[6:7], v[28:29]
	v_pk_mul_f32 v[2:3], v[2:3], v[28:29]
	global_store_dwordx4 v[4:5], v[8:11], off
	v_mul_f32_e32 v6, 0xbdd2d3e7, v16
	v_mul_f32_e32 v7, 0xbdd2d3e7, v17
	v_mul_f32_e32 v8, 0xbdd2d3e7, v0
	v_mul_f32_e32 v9, 0xbdd2d3e7, v1
	v_mul_f32_e32 v10, 0xbdd2d3e7, v12
	v_mul_f32_e32 v11, 0xbdd2d3e7, v13
	v_mul_f32_e32 v14, 0xbdd2d3e7, v2
	v_mul_f32_e32 v15, 0xbdd2d3e7, v3
	v_fmaak_f32 v6, v16, v6, 0xc0135761
	v_fmaak_f32 v7, v17, v7, 0xc0135761
	v_fmaak_f32 v8, v0, v8, 0xc0135761
	v_fmaak_f32 v9, v1, v9, 0xc0135761
	v_fmaak_f32 v10, v12, v10, 0xc0135761
	v_fmaak_f32 v11, v13, v11, 0xc0135761
	v_fmaak_f32 v14, v2, v14, 0xc0135761
	v_fmaak_f32 v15, v3, v15, 0xc0135761
	v_mul_f32_e32 v6, v16, v6
	v_mul_f32_e32 v7, v17, v7
	v_mul_f32_e32 v8, v0, v8
	v_mul_f32_e32 v9, v1, v9
	v_mul_f32_e32 v10, v12, v10
	v_mul_f32_e32 v11, v13, v11
	v_mul_f32_e32 v14, v2, v14
	v_mul_f32_e32 v15, v3, v15
	v_exp_f32_e32 v6, v6
	v_exp_f32_e32 v7, v7
	v_exp_f32_e32 v8, v8
	v_exp_f32_e32 v9, v9
	v_exp_f32_e32 v10, v10
	v_exp_f32_e32 v11, v11
	v_exp_f32_e32 v14, v14
	v_exp_f32_e32 v15, v15
	v_add_f32_e32 v6, 1.0, v6
	v_add_f32_e32 v7, 1.0, v7
	v_add_f32_e32 v8, 1.0, v8
	v_add_f32_e32 v9, 1.0, v9
	v_add_f32_e32 v10, 1.0, v10
	v_add_f32_e32 v11, 1.0, v11
	v_add_f32_e32 v14, 1.0, v14
	v_add_f32_e32 v15, 1.0, v15
	v_rcp_f32_e32 v6, v6
	v_rcp_f32_e32 v7, v7
	v_rcp_f32_e32 v8, v8
	v_rcp_f32_e32 v9, v9
	v_rcp_f32_e32 v10, v10
	v_rcp_f32_e32 v11, v11
	v_rcp_f32_e32 v14, v14
	v_rcp_f32_e32 v15, v15
	v_pk_mul_f32 v[6:7], v[16:17], v[6:7]
	v_pk_mul_f32 v[8:9], v[0:1], v[8:9]
	v_pk_mul_f32 v[10:11], v[12:13], v[10:11]
	v_pk_mul_f32 v[12:13], v[2:3], v[14:15]
	v_cvt_pk_bf16_f32 v0, v6, v7
	v_cvt_pk_bf16_f32 v1, v8, v9
	v_cvt_pk_bf16_f32 v2, v10, v11
	v_cvt_pk_bf16_f32 v3, v12, v13
	global_store_dwordx4 v[4:5], v[0:3], off offset:256
	s_branch .LBB0_314
